# wo K-loop: LDS fragment reads double-buffered one k16 step ahead; hyena spectrum multiply: 8 loads in flight per iteration
# speedup vs baseline: 1.0089x; 1.0089x over previous
; DI float2 cmul(float2 a, float2 b) { return make_float2(a.x * b.x - a.y * b.y, a.x * b.y + a.y * b.x); }
; DI void hyena_lat_item(const P& p, int l, int c, int bp, unsigned char* lds) {
;     ...
; #pragma unroll 8
;     for (int i = tid; i < 16384; i += NT) { s[phys(i)] = cmul(s[phys(i)], H[i]); }
.LBB0_482:
	v_add_co_u32_e32 v194, vcc, 0xffff9ffc, v4
	v_ashrrev_i32_e32 v202, 4, v2
	v_add_u32_e32 v203, 0x200, v2
	v_addc_co_u32_e32 v195, vcc, -1, v5, vcc
	v_ashrrev_i32_e32 v203, 4, v203
	global_load_dwordx2 v[130:131], v[194:195], off offset:-4096
	global_load_dwordx2 v[132:133], v[194:195], off
	v_lshl_add_u32 v202, v202, 3, v1
	v_lshl_add_u32 v203, v203, 3, v1
	v_add_co_u32_e32 v196, vcc, 0xffffbffc, v4
	v_add_u32_e32 v204, 0x400, v2
	v_add_u32_e32 v205, 0x600, v2
	v_addc_co_u32_e32 v197, vcc, -1, v5, vcc
	v_ashrrev_i32_e32 v204, 4, v204
	v_ashrrev_i32_e32 v205, 4, v205
	global_load_dwordx2 v[134:135], v[196:197], off offset:-4096
	global_load_dwordx2 v[136:137], v[196:197], off
	v_lshl_add_u32 v204, v204, 3, v1
	v_lshl_add_u32 v205, v205, 3, v1
	v_add_co_u32_e32 v198, vcc, 0xffffdffc, v4
	v_add_u32_e32 v206, 0x800, v2
	v_add_u32_e32 v207, 0xa00, v2
	v_addc_co_u32_e32 v199, vcc, -1, v5, vcc
	v_ashrrev_i32_e32 v206, 4, v206
	v_ashrrev_i32_e32 v207, 4, v207
	global_load_dwordx2 v[138:139], v[198:199], off offset:-4096
	global_load_dwordx2 v[140:141], v[198:199], off
	v_lshl_add_u32 v206, v206, 3, v1
	v_lshl_add_u32 v207, v207, 3, v1
	v_add_co_u32_e32 v200, vcc, 0xfffffffc, v4
	v_add_u32_e32 v208, 0xc00, v2
	v_add_u32_e32 v209, 0xe00, v2
	v_addc_co_u32_e32 v201, vcc, -1, v5, vcc
	v_ashrrev_i32_e32 v208, 4, v208
	v_ashrrev_i32_e32 v209, 4, v209
	global_load_dwordx2 v[142:143], v[200:201], off offset:-4096
	global_load_dwordx2 v[144:145], v[200:201], off
	v_lshl_add_u32 v208, v208, 3, v1
	v_lshl_add_u32 v209, v209, 3, v1
	ds_read_b64 v[146:147], v202
	ds_read_b64 v[148:149], v203 offset:4096
	ds_read_b64 v[150:151], v204 offset:8192
	ds_read_b64 v[152:153], v205 offset:12288
	ds_read_b64 v[154:155], v206 offset:16384
	ds_read_b64 v[156:157], v207 offset:20480
	ds_read_b64 v[158:159], v208 offset:24576
	ds_read_b64 v[160:161], v209 offset:28672
	v_cmp_lt_i32_e32 vcc, s20, v2
	s_or_b64 s[10:11], vcc, s[10:11]
	v_add_u32_e32 v1, 0x8000, v1
	v_lshl_add_u64 v[4:5], v[4:5], 0, s[22:23]
	v_add_u32_e32 v2, 0x1000, v2
	s_waitcnt vmcnt(7) lgkmcnt(7)
	v_pk_mul_f32 v[232:233], v[146:147], v[130:131] op_sel:[1,1] op_sel_hi:[0,1]
	v_pk_fma_f32 v[234:235], v[146:147], v[130:131], v[232:233] neg_lo:[0,0,1] neg_hi:[0,0,1]
	v_pk_fma_f32 v[130:131], v[146:147], v[130:131], v[232:233] op_sel_hi:[1,0,1]
	s_nop 0
	v_mov_b32_e32 v235, v131
	ds_write_b64 v202, v[234:235]
	s_waitcnt vmcnt(6) lgkmcnt(7)
	v_pk_mul_f32 v[232:233], v[148:149], v[132:133] op_sel:[1,1] op_sel_hi:[0,1]
	v_pk_fma_f32 v[234:235], v[148:149], v[132:133], v[232:233] neg_lo:[0,0,1] neg_hi:[0,0,1]
	v_pk_fma_f32 v[132:133], v[148:149], v[132:133], v[232:233] op_sel_hi:[1,0,1]
	s_nop 0
	v_mov_b32_e32 v235, v133
	ds_write_b64 v203, v[234:235] offset:4096
	s_waitcnt vmcnt(5) lgkmcnt(7)
	v_pk_mul_f32 v[232:233], v[150:151], v[134:135] op_sel:[1,1] op_sel_hi:[0,1]
	v_pk_fma_f32 v[234:235], v[150:151], v[134:135], v[232:233] neg_lo:[0,0,1] neg_hi:[0,0,1]
	v_pk_fma_f32 v[134:135], v[150:151], v[134:135], v[232:233] op_sel_hi:[1,0,1]
	s_nop 0
	v_mov_b32_e32 v235, v135
	ds_write_b64 v204, v[234:235] offset:8192
	s_waitcnt vmcnt(4) lgkmcnt(7)
	v_pk_mul_f32 v[232:233], v[152:153], v[136:137] op_sel:[1,1] op_sel_hi:[0,1]
	v_pk_fma_f32 v[234:235], v[152:153], v[136:137], v[232:233] neg_lo:[0,0,1] neg_hi:[0,0,1]
	v_pk_fma_f32 v[136:137], v[152:153], v[136:137], v[232:233] op_sel_hi:[1,0,1]
	s_nop 0
	v_mov_b32_e32 v235, v137
	ds_write_b64 v205, v[234:235] offset:12288
	s_waitcnt vmcnt(3) lgkmcnt(7)
	v_pk_mul_f32 v[232:233], v[154:155], v[138:139] op_sel:[1,1] op_sel_hi:[0,1]
	v_pk_fma_f32 v[234:235], v[154:155], v[138:139], v[232:233] neg_lo:[0,0,1] neg_hi:[0,0,1]
	v_pk_fma_f32 v[138:139], v[154:155], v[138:139], v[232:233] op_sel_hi:[1,0,1]
	s_nop 0
	v_mov_b32_e32 v235, v139
	ds_write_b64 v206, v[234:235] offset:16384
	s_waitcnt vmcnt(2) lgkmcnt(7)
	v_pk_mul_f32 v[232:233], v[156:157], v[140:141] op_sel:[1,1] op_sel_hi:[0,1]
	v_pk_fma_f32 v[234:235], v[156:157], v[140:141], v[232:233] neg_lo:[0,0,1] neg_hi:[0,0,1]
	v_pk_fma_f32 v[140:141], v[156:157], v[140:141], v[232:233] op_sel_hi:[1,0,1]
	s_nop 0
	v_mov_b32_e32 v235, v141
	ds_write_b64 v207, v[234:235] offset:20480
	s_waitcnt vmcnt(1) lgkmcnt(7)
	v_pk_mul_f32 v[232:233], v[158:159], v[142:143] op_sel:[1,1] op_sel_hi:[0,1]
	v_pk_fma_f32 v[234:235], v[158:159], v[142:143], v[232:233] neg_lo:[0,0,1] neg_hi:[0,0,1]
	v_pk_fma_f32 v[142:143], v[158:159], v[142:143], v[232:233] op_sel_hi:[1,0,1]
	s_nop 0
	v_mov_b32_e32 v235, v143
	ds_write_b64 v208, v[234:235] offset:24576
	s_waitcnt vmcnt(0) lgkmcnt(7)
	v_pk_mul_f32 v[232:233], v[160:161], v[144:145] op_sel:[1,1] op_sel_hi:[0,1]
	v_pk_fma_f32 v[234:235], v[160:161], v[144:145], v[232:233] neg_lo:[0,0,1] neg_hi:[0,0,1]
	v_pk_fma_f32 v[144:145], v[160:161], v[144:145], v[232:233] op_sel_hi:[1,0,1]
	s_nop 0
	v_mov_b32_e32 v235, v145
	ds_write_b64 v209, v[234:235] offset:28672
	s_andn2_b64 exec, exec, s[10:11]
	s_cbranch_execnz .LBB0_482

; DI float2 cmul(float2 a, float2 b) { return make_float2(a.x * b.x - a.y * b.y, a.x * b.y + a.y * b.x); }
; DI void hyena_lat_item(const P& p, int l, int c, int bp, unsigned char* lds) {
;     ...
; #pragma unroll 8
;     for (int i = tid; i < 16384; i += NT) { s[phys(i)] = cmul(s[phys(i)], H[i]); }
.LBB0_498:
	v_add_co_u32_e32 v194, vcc, 0xffff9ffc, v2
	v_ashrrev_i32_e32 v202, 4, v52
	v_add_u32_e32 v203, 0x200, v52
	v_addc_co_u32_e32 v195, vcc, -1, v3, vcc
	v_ashrrev_i32_e32 v203, 4, v203
	global_load_dwordx2 v[130:131], v[194:195], off offset:-4096
	global_load_dwordx2 v[132:133], v[194:195], off
	v_lshl_add_u32 v202, v202, 3, v4
	v_lshl_add_u32 v203, v203, 3, v4
	v_add_co_u32_e32 v196, vcc, 0xffffbffc, v2
	v_add_u32_e32 v204, 0x400, v52
	v_add_u32_e32 v205, 0x600, v52
	v_addc_co_u32_e32 v197, vcc, -1, v3, vcc
	v_ashrrev_i32_e32 v204, 4, v204
	v_ashrrev_i32_e32 v205, 4, v205
	global_load_dwordx2 v[134:135], v[196:197], off offset:-4096
	global_load_dwordx2 v[136:137], v[196:197], off
	v_lshl_add_u32 v204, v204, 3, v4
	v_lshl_add_u32 v205, v205, 3, v4
	v_add_co_u32_e32 v198, vcc, 0xffffdffc, v2
	v_add_u32_e32 v206, 0x800, v52
	v_add_u32_e32 v207, 0xa00, v52
	v_addc_co_u32_e32 v199, vcc, -1, v3, vcc
	v_ashrrev_i32_e32 v206, 4, v206
	v_ashrrev_i32_e32 v207, 4, v207
	global_load_dwordx2 v[138:139], v[198:199], off offset:-4096
	global_load_dwordx2 v[140:141], v[198:199], off
	v_lshl_add_u32 v206, v206, 3, v4
	v_lshl_add_u32 v207, v207, 3, v4
	v_add_co_u32_e32 v200, vcc, 0xfffffffc, v2
	v_add_u32_e32 v208, 0xc00, v52
	v_add_u32_e32 v209, 0xe00, v52
	v_addc_co_u32_e32 v201, vcc, -1, v3, vcc
	v_ashrrev_i32_e32 v208, 4, v208
	v_ashrrev_i32_e32 v209, 4, v209
	global_load_dwordx2 v[142:143], v[200:201], off offset:-4096
	global_load_dwordx2 v[144:145], v[200:201], off
	v_lshl_add_u32 v208, v208, 3, v4
	v_lshl_add_u32 v209, v209, 3, v4
	ds_read_b64 v[146:147], v202
	ds_read_b64 v[148:149], v203 offset:4096
	ds_read_b64 v[150:151], v204 offset:8192
	ds_read_b64 v[152:153], v205 offset:12288
	ds_read_b64 v[154:155], v206 offset:16384
	ds_read_b64 v[156:157], v207 offset:20480
	ds_read_b64 v[158:159], v208 offset:24576
	ds_read_b64 v[160:161], v209 offset:28672
	v_cmp_lt_i32_e32 vcc, s18, v52
	s_or_b64 s[4:5], vcc, s[4:5]
	v_add_u32_e32 v4, 0x8000, v4
	v_lshl_add_u64 v[2:3], v[2:3], 0, s[20:21]
	v_add_u32_e32 v52, 0x1000, v52
	s_waitcnt vmcnt(7) lgkmcnt(7)
	v_pk_mul_f32 v[232:233], v[146:147], v[130:131] op_sel:[1,1] op_sel_hi:[0,1]
	v_pk_fma_f32 v[234:235], v[146:147], v[130:131], v[232:233] neg_lo:[0,0,1] neg_hi:[0,0,1]
	v_pk_fma_f32 v[130:131], v[146:147], v[130:131], v[232:233] op_sel_hi:[1,0,1]
	s_nop 0
	v_mov_b32_e32 v235, v131
	ds_write_b64 v202, v[234:235]
	s_waitcnt vmcnt(6) lgkmcnt(7)
	v_pk_mul_f32 v[232:233], v[148:149], v[132:133] op_sel:[1,1] op_sel_hi:[0,1]
	v_pk_fma_f32 v[234:235], v[148:149], v[132:133], v[232:233] neg_lo:[0,0,1] neg_hi:[0,0,1]
	v_pk_fma_f32 v[132:133], v[148:149], v[132:133], v[232:233] op_sel_hi:[1,0,1]
	s_nop 0
	v_mov_b32_e32 v235, v133
	ds_write_b64 v203, v[234:235] offset:4096
	s_waitcnt vmcnt(5) lgkmcnt(7)
	v_pk_mul_f32 v[232:233], v[150:151], v[134:135] op_sel:[1,1] op_sel_hi:[0,1]
	v_pk_fma_f32 v[234:235], v[150:151], v[134:135], v[232:233] neg_lo:[0,0,1] neg_hi:[0,0,1]
	v_pk_fma_f32 v[134:135], v[150:151], v[134:135], v[232:233] op_sel_hi:[1,0,1]
	s_nop 0
	v_mov_b32_e32 v235, v135
	ds_write_b64 v204, v[234:235] offset:8192
	s_waitcnt vmcnt(4) lgkmcnt(7)
	v_pk_mul_f32 v[232:233], v[152:153], v[136:137] op_sel:[1,1] op_sel_hi:[0,1]
	v_pk_fma_f32 v[234:235], v[152:153], v[136:137], v[232:233] neg_lo:[0,0,1] neg_hi:[0,0,1]
	v_pk_fma_f32 v[136:137], v[152:153], v[136:137], v[232:233] op_sel_hi:[1,0,1]
	s_nop 0
	v_mov_b32_e32 v235, v137
	ds_write_b64 v205, v[234:235] offset:12288
	s_waitcnt vmcnt(3) lgkmcnt(7)
	v_pk_mul_f32 v[232:233], v[154:155], v[138:139] op_sel:[1,1] op_sel_hi:[0,1]
	v_pk_fma_f32 v[234:235], v[154:155], v[138:139], v[232:233] neg_lo:[0,0,1] neg_hi:[0,0,1]
	v_pk_fma_f32 v[138:139], v[154:155], v[138:139], v[232:233] op_sel_hi:[1,0,1]
	s_nop 0
	v_mov_b32_e32 v235, v139
	ds_write_b64 v206, v[234:235] offset:16384
	s_waitcnt vmcnt(2) lgkmcnt(7)
	v_pk_mul_f32 v[232:233], v[156:157], v[140:141] op_sel:[1,1] op_sel_hi:[0,1]
	v_pk_fma_f32 v[234:235], v[156:157], v[140:141], v[232:233] neg_lo:[0,0,1] neg_hi:[0,0,1]
	v_pk_fma_f32 v[140:141], v[156:157], v[140:141], v[232:233] op_sel_hi:[1,0,1]
	s_nop 0
	v_mov_b32_e32 v235, v141
	ds_write_b64 v207, v[234:235] offset:20480
	s_waitcnt vmcnt(1) lgkmcnt(7)
	v_pk_mul_f32 v[232:233], v[158:159], v[142:143] op_sel:[1,1] op_sel_hi:[0,1]
	v_pk_fma_f32 v[234:235], v[158:159], v[142:143], v[232:233] neg_lo:[0,0,1] neg_hi:[0,0,1]
	v_pk_fma_f32 v[142:143], v[158:159], v[142:143], v[232:233] op_sel_hi:[1,0,1]
	s_nop 0
	v_mov_b32_e32 v235, v143
	ds_write_b64 v208, v[234:235] offset:24576
	s_waitcnt vmcnt(0) lgkmcnt(7)
	v_pk_mul_f32 v[232:233], v[160:161], v[144:145] op_sel:[1,1] op_sel_hi:[0,1]
	v_pk_fma_f32 v[234:235], v[160:161], v[144:145], v[232:233] neg_lo:[0,0,1] neg_hi:[0,0,1]
	v_pk_fma_f32 v[144:145], v[160:161], v[144:145], v[232:233] op_sel_hi:[1,0,1]
	s_nop 0
	v_mov_b32_e32 v235, v145
	ds_write_b64 v209, v[234:235] offset:28672
	s_andn2_b64 exec, exec, s[4:5]
	s_cbranch_execnz .LBB0_498

; DI int otid() { int t = threadIdx.x; asm volatile("" : "+v"(t)); return t; }
; #define G_LOADR(S, ko) do { S##0 = *(const uint4*)(a0p + (ko)); S##1 = *(const uint4*)(a1p + (ko)); S##2 = *(const uint4*)(a2p + (ko)); \
;     S##3 = *(const uint4*)(a3p + (ko)); S##4 = *(const uint4*)(b0p + (ko)); S##5 = *(const uint4*)(b1p + (ko)); } while (0)
; #define G_STORER(S, nb) do { *(uint4*)((nb) + wofs) = S##0; *(uint4*)((nb) + wofs + 64 * G_AST) = S##1; *(uint4*)((nb) + wofs + 128 * G_AST) = S##2; \
;     *(uint4*)((nb) + wofs + 192 * G_AST) = S##3; *(uint4*)((nb) + G_ABYTES + wofs) = S##4; *(uint4*)((nb) + G_ABYTES + wofs + 64 * G_AST) = S##5; } while (0)
; DI void gemm_main(f32x16 (&acc)[2][2], const u16* const (&ap)[4], const u16* const (&bp)[2], int K, unsigned char* lds) {
;   const int tid = otid(), lane = tid & 63, w = tid >> 6, r = lane & 31, hh = lane >> 5;
;   const int wm = w >> 1, wn = w & 1;
;   const int wofs = (tid >> 3) * G_AST + (tid & 7) * 16;
;   const u16* a0p = ap[0]; const u16* a1p = ap[1]; const u16* a2p = ap[2]; const u16* a3p = ap[3];
;   const u16* b0p = bp[0]; const u16* b1p = bp[1];
;   uint4 P0, P1, P2, P3, P4, P5, Q0, Q1, Q2, Q3, Q4, Q5;
;   G_LOADR(P, 0);
;   G_LOADR(Q, 64);
;   G_STORER(P, lds);
;   __syncthreads();
;   const unsigned char* As0 = lds + (wm * 64 + r) * G_AST + hh * 16;
;   const unsigned char* Bs0 = lds + G_ABYTES + (wn * 64 + r) * G_AST + hh * 16;
;   const int nk = K >> 6;
;   for (int kt = 0; kt < nk; kt += 2) {
;     if (kt + 2 < nk) G_LOADR(P, (kt + 2) * 64);
;     __builtin_amdgcn_sched_barrier(0);
;     gemm_compute(acc, As0, Bs0);
;     __builtin_amdgcn_sched_barrier(0);
;     G_STORER(Q, lds + G_STAGE);
;     __syncthreads();
; template <class F>
; DI void for_tiles(int ntm, int ntn, F f) {
;   const int xcd = blockIdx.x & 7, lb = blockIdx.x >> 3, nlb = gridDim.x >> 3;
;   const int total = ((ntm + 3) & ~3) * ntn;
;   const int chunk = (total + 7) >> 3;
;   for (int i = lb; i < chunk; i += nlb) {
;     int idx = xcd * chunk + i;
;     if (idx >= total) break;
;     int panel = idx / (4 * ntn), within = idx - panel * 4 * ntn;
;     int n = within >> 2, m = panel * 4 + (within & 3);
;     if (m < ntm) f(m, n);
.LBB0_678:
	s_add_i32 s4, s79, s10
	s_cmp_ge_u32 s4, s78
	s_mov_b64 s[0:1], -1
	s_cbranch_scc1 .LBB0_677
	s_lshr_b32 s0, s4, 3
	s_and_b32 s0, s0, 0xffffffc
	s_and_b32 s1, s10, 3
	s_or_b32 s0, s0, s1
	s_cmp_ge_u32 s0, s43
	s_cbranch_scc1 .LBB0_676
	v_mov_b32_e32 v3, v215
	s_lshl_b32 s11, s0, 8
	v_readlane_b32 s4, v253, 28
	v_ashrrev_i32_e32 v2, 3, v3
	v_add_u32_e32 v2, s11, v2
	v_lshlrev_b32_e32 v3, 4, v3
	v_and_b32_e32 v178, 0x70, v3
	v_readlane_b32 s5, v253, 29
	v_ashrrev_i32_e32 v3, 31, v2
	s_lshl_b32 s1, s8, 5
	v_lshl_add_u64 v[4:5], s[4:5], 0, v[178:179]
	v_lshlrev_b64 v[2:3], 11, v[2:3]
	s_and_b32 s1, s1, 0xfffffc00
	v_lshl_add_u64 v[114:115], v[4:5], 0, v[2:3]
	s_sub_i32 s1, s9, s1
	v_add_co_u32_e32 v6, vcc, s51, v114
	s_and_b32 s0, s1, 0xffffff80
	v_mov_b32_e32 v3, v215
	v_addc_co_u32_e32 v7, vcc, 0, v115, vcc
	s_mov_b32 s1, 0x40000
	v_add_co_u32_e32 v10, vcc, s1, v114
	v_ashrrev_i32_e32 v2, 3, v3
	v_add_u32_e32 v2, s0, v2
	v_lshlrev_b32_e32 v3, 4, v3
	v_addc_co_u32_e32 v11, vcc, 0, v115, vcc
	s_mov_b32 s1, 0x60000
	v_and_b32_e32 v178, 0x70, v3
	v_ashrrev_i32_e32 v3, 31, v2
	v_add_co_u32_e32 v14, vcc, s1, v114
	v_lshl_add_u64 v[4:5], s[6:7], 0, v[178:179]
	v_lshlrev_b64 v[2:3], 11, v[2:3]
	v_mov_b32_e32 v26, v215
	v_addc_co_u32_e32 v15, vcc, 0, v115, vcc
	v_lshl_add_u64 v[116:117], v[4:5], 0, v[2:3]
	global_load_dwordx4 v[2:5], v[114:115], off
	s_nop 0
	global_load_dwordx4 v[6:9], v[6:7], off
	s_nop 0
	global_load_dwordx4 v[10:13], v[10:11], off
	s_nop 0
	global_load_dwordx4 v[14:17], v[14:15], off
	s_nop 0
	global_load_dwordx4 v[18:21], v[116:117], off
	v_add_co_u32_e32 v22, vcc, s51, v116
	v_lshrrev_b32_e32 v27, 3, v26
	s_nop 0
	v_addc_co_u32_e32 v23, vcc, 0, v117, vcc
	global_load_dwordx4 v[22:25], v[22:23], off
	v_lshlrev_b32_e32 v28, 4, v26
	v_mul_lo_u32 v27, v27, s37
	v_and_b32_e32 v28, 0x70, v28
	s_mov_b64 s[12:13], 0x20000
	s_mov_b64 s[4:5], 0x40000
	v_add3_u32 v129, v27, v28, 0
	v_lshl_add_u64 v[118:119], v[114:115], 0, s[12:13]
	v_lshl_add_u64 v[120:121], v[114:115], 0, s[4:5]
	s_mov_b64 s[4:5], 0x60000
	v_lshl_add_u64 v[122:123], v[114:115], 0, s[4:5]
	global_load_dwordx4 v[90:93], v[114:115], off offset:128
	v_lshl_add_u64 v[124:125], v[116:117], 0, s[12:13]
	global_load_dwordx4 v[94:97], v[118:119], off offset:128
	global_load_dwordx4 v[98:101], v[120:121], off offset:128
	global_load_dwordx4 v[102:105], v[122:123], off offset:128
	global_load_dwordx4 v[106:109], v[116:117], off offset:128
	global_load_dwordx4 v[110:113], v[124:125], off offset:128
	s_mov_b32 s1, 0xfffffc0
	v_add_u32_e32 v131, 0xd800, v129
	v_add_u32_e32 v130, 0x16800, v129
	s_waitcnt vmcnt(0)
	ds_write_b128 v129, v[2:5]
	ds_write_b128 v129, v[6:9] offset:9216
	ds_write_b128 v129, v[10:13] offset:18432
	ds_write_b128 v129, v[14:17] offset:27648
	ds_write_b128 v129, v[18:21] offset:36864
	ds_write_b128 v129, v[22:25] offset:46080
	s_waitcnt lgkmcnt(0)
	s_barrier
	global_load_dwordx4 v[66:69], v[114:115], off offset:256
	global_load_dwordx4 v[70:73], v[118:119], off offset:256
	global_load_dwordx4 v[74:77], v[120:121], off offset:256
	global_load_dwordx4 v[78:81], v[122:123], off offset:256
	global_load_dwordx4 v[82:85], v[116:117], off offset:256
	global_load_dwordx4 v[86:89], v[124:125], off offset:256
	v_and_b32_e32 v2, 31, v26
	v_lshrrev_b32_e32 v3, 1, v26
	v_and_or_b32 v2, v3, s1, v2
	v_mul_lo_u32 v2, v2, s37
	v_and_b32_e32 v3, 16, v3
	v_add3_u32 v127, 0, v2, v3
	v_and_b32_e32 v2, 0x5f, v26
	v_mul_u32_u24_e32 v2, 0x90, v2
	v_add3_u32 v132, 0, v2, v3
	v_add_u32_e32 v128, 0x9000, v132
	ds_read_b128 v[2:5], v127
	ds_read_b128 v[6:9], v132 offset:36864
	ds_read_b128 v[10:13], v132 offset:41472
	s_waitcnt lgkmcnt(1)
	v_mfma_f32_32x32x16_bf16 v[50:65], v[2:5], v[6:9], 0
	s_waitcnt lgkmcnt(0)
	v_mfma_f32_32x32x16_bf16 v[34:49], v[2:5], v[10:13], 0
	ds_read_b128 v[2:5], v127 offset:4608
	ds_read_b128 v[134:137], v127 offset:32
	ds_read_b128 v[138:141], v132 offset:36896
	ds_read_b128 v[142:145], v132 offset:41504
	s_waitcnt lgkmcnt(1)
	v_mfma_f32_32x32x16_bf16 v[50:65], v[134:137], v[138:141], v[50:65]
	s_waitcnt lgkmcnt(0)
	v_mfma_f32_32x32x16_bf16 v[34:49], v[134:137], v[142:145], v[34:49]
	ds_read_b128 v[134:137], v127 offset:4640
	v_mfma_f32_32x32x16_bf16 v[18:33], v[2:5], v[6:9], 0
	v_mfma_f32_32x32x16_bf16 v[2:17], v[2:5], v[10:13], 0
	s_waitcnt lgkmcnt(0)
	v_mfma_f32_32x32x16_bf16 v[18:33], v[134:137], v[138:141], v[18:33]
	v_mfma_f32_32x32x16_bf16 v[2:17], v[134:137], v[142:145], v[2:17]
	ds_read_b128 v[134:137], v127 offset:64
	ds_read_b128 v[138:141], v132 offset:36928
	ds_read_b128 v[142:145], v132 offset:41536
	s_waitcnt lgkmcnt(1)
	v_mfma_f32_32x32x16_bf16 v[50:65], v[134:137], v[138:141], v[50:65]
	s_waitcnt lgkmcnt(0)
	v_mfma_f32_32x32x16_bf16 v[34:49], v[134:137], v[142:145], v[34:49]
	ds_read_b128 v[134:137], v127 offset:4672
	s_waitcnt lgkmcnt(0)
	v_mfma_f32_32x32x16_bf16 v[18:33], v[134:137], v[138:141], v[18:33]
	v_mfma_f32_32x32x16_bf16 v[2:17], v[134:137], v[142:145], v[2:17]
	ds_read_b128 v[134:137], v127 offset:96
	ds_read_b128 v[138:141], v132 offset:36960
	ds_read_b128 v[142:145], v132 offset:41568
	s_waitcnt lgkmcnt(1)
	v_mfma_f32_32x32x16_bf16 v[50:65], v[134:137], v[138:141], v[50:65]
	s_waitcnt lgkmcnt(0)
	v_mfma_f32_32x32x16_bf16 v[34:49], v[134:137], v[142:145], v[34:49]
	ds_read_b128 v[134:137], v127 offset:4704
	s_waitcnt lgkmcnt(0)
	v_mfma_f32_32x32x16_bf16 v[18:33], v[134:137], v[138:141], v[18:33]
	v_mfma_f32_32x32x16_bf16 v[2:17], v[134:137], v[142:145], v[2:17]
	ds_write_b128 v129, v[90:93] offset:55296
	ds_write_b128 v129, v[94:97] offset:64512
	ds_write_b128 v131, v[98:101] offset:18432
	ds_write_b128 v131, v[102:105] offset:27648
	ds_write_b128 v130, v[106:109]
	ds_write_b128 v130, v[110:113] offset:9216
	s_waitcnt lgkmcnt(0)
	s_barrier
; #define MFMA16(a, b, c) __builtin_amdgcn_mfma_f32_32x32x16_bf16((a), (b), (c), 0, 0, 0)
; #define G_LOADR(S, ko) do { S##0 = *(const uint4*)(a0p + (ko)); S##1 = *(const uint4*)(a1p + (ko)); S##2 = *(const uint4*)(a2p + (ko)); \
;     S##3 = *(const uint4*)(a3p + (ko)); S##4 = *(const uint4*)(b0p + (ko)); S##5 = *(const uint4*)(b1p + (ko)); } while (0)
; #define G_STORER(S, nb) do { *(uint4*)((nb) + wofs) = S##0; *(uint4*)((nb) + wofs + 64 * G_AST) = S##1; *(uint4*)((nb) + wofs + 128 * G_AST) = S##2; \
;     *(uint4*)((nb) + wofs + 192 * G_AST) = S##3; *(uint4*)((nb) + G_ABYTES + wofs) = S##4; *(uint4*)((nb) + G_ABYTES + wofs + 64 * G_AST) = S##5; } while (0)
; DI void gemm_compute(f32x16 (&acc)[2][2], const unsigned char* As, const unsigned char* Bs) {
;   bf16x8 a0 = *(const bf16x8*)(As), a1 = *(const bf16x8*)(As + 32 * G_AST);
;   bf16x8 b0 = *(const bf16x8*)(Bs), b1 = *(const bf16x8*)(Bs + 32 * G_AST);
; #pragma unroll
;   for (int ks = 0; ks < 4; ++ks) {
;     bf16x8 na0 = a0, na1 = a1, nb0 = b0, nb1 = b1;
;     if (ks < 3) {
;       na0 = *(const bf16x8*)(As + (ks + 1) * 32); na1 = *(const bf16x8*)(As + 32 * G_AST + (ks + 1) * 32);
;       nb0 = *(const bf16x8*)(Bs + (ks + 1) * 32); nb1 = *(const bf16x8*)(Bs + 32 * G_AST + (ks + 1) * 32);
;     }
;     acc[0][0] = MFMA16(a0, b0, acc[0][0]);
;     acc[0][1] = MFMA16(a0, b1, acc[0][1]);
;     acc[1][0] = MFMA16(a1, b0, acc[1][0]);
;     acc[1][1] = MFMA16(a1, b1, acc[1][1]);
;     a0 = na0; a1 = na1; b0 = nb0; b1 = nb1;
;   }
; }
; DI void gemm_main(f32x16 (&acc)[2][2], const u16* const (&ap)[4], const u16* const (&bp)[2], int K, unsigned char* lds) {
;     ...
;   for (int kt = 0; kt < nk; kt += 2) {
;     if (kt + 2 < nk) G_LOADR(P, (kt + 2) * 64);
;     __builtin_amdgcn_sched_barrier(0);
;     gemm_compute(acc, As0, Bs0);
;     __builtin_amdgcn_sched_barrier(0);
;     G_STORER(Q, lds + G_STAGE);
;     __syncthreads();
;     if (kt + 3 < nk) G_LOADR(Q, (kt + 3) * 64);
;     __builtin_amdgcn_sched_barrier(0);
;     gemm_compute(acc, As0 + G_STAGE, Bs0 + G_STAGE);
;     __builtin_amdgcn_sched_barrier(0);
;     if (kt + 2 < nk) G_STORER(P, lds);
;     __syncthreads();
	global_load_dwordx4 v[90:93], v[114:115], off offset:384
	global_load_dwordx4 v[94:97], v[118:119], off offset:384
	global_load_dwordx4 v[98:101], v[120:121], off offset:384
	global_load_dwordx4 v[102:105], v[122:123], off offset:384
	global_load_dwordx4 v[106:109], v[116:117], off offset:384
	global_load_dwordx4 v[110:113], v[124:125], off offset:384
	ds_read_b128 v[146:149], v127 offset:55296
	ds_read_b128 v[154:157], v128 offset:55296
	ds_read_b128 v[158:161], v128 offset:59904
	ds_read_b128 v[150:153], v127 offset:59904
	ds_read_b128 v[194:197], v127 offset:55328
	ds_read_b128 v[202:205], v128 offset:55328
	ds_read_b128 v[206:209], v128 offset:59936
	ds_read_b128 v[198:201], v127 offset:59936
	s_waitcnt lgkmcnt(4)
	v_mfma_f32_32x32x16_bf16 v[50:65], v[146:149], v[154:157], v[50:65]
	v_mfma_f32_32x32x16_bf16 v[34:49], v[146:149], v[158:161], v[34:49]
	v_mfma_f32_32x32x16_bf16 v[18:33], v[150:153], v[154:157], v[18:33]
	v_mfma_f32_32x32x16_bf16 v[2:17], v[150:153], v[158:161], v[2:17]
	ds_read_b128 v[146:149], v127 offset:55360
	ds_read_b128 v[154:157], v128 offset:55360
	ds_read_b128 v[158:161], v128 offset:59968
	ds_read_b128 v[150:153], v127 offset:59968
	s_waitcnt lgkmcnt(4)
	v_mfma_f32_32x32x16_bf16 v[50:65], v[194:197], v[202:205], v[50:65]
	v_mfma_f32_32x32x16_bf16 v[34:49], v[194:197], v[206:209], v[34:49]
	v_mfma_f32_32x32x16_bf16 v[18:33], v[198:201], v[202:205], v[18:33]
	v_mfma_f32_32x32x16_bf16 v[2:17], v[198:201], v[206:209], v[2:17]
	ds_read_b128 v[194:197], v127 offset:55392
	ds_read_b128 v[202:205], v128 offset:55392
	ds_read_b128 v[206:209], v128 offset:60000
	ds_read_b128 v[198:201], v127 offset:60000
	s_waitcnt lgkmcnt(4)
	v_mfma_f32_32x32x16_bf16 v[50:65], v[146:149], v[154:157], v[50:65]
	v_mfma_f32_32x32x16_bf16 v[34:49], v[146:149], v[158:161], v[34:49]
	v_mfma_f32_32x32x16_bf16 v[18:33], v[150:153], v[154:157], v[18:33]
	v_mfma_f32_32x32x16_bf16 v[2:17], v[150:153], v[158:161], v[2:17]
	s_waitcnt lgkmcnt(0)
	v_mfma_f32_32x32x16_bf16 v[50:65], v[194:197], v[202:205], v[50:65]
	v_mfma_f32_32x32x16_bf16 v[34:49], v[194:197], v[206:209], v[34:49]
	v_mfma_f32_32x32x16_bf16 v[18:33], v[198:201], v[202:205], v[18:33]
	v_mfma_f32_32x32x16_bf16 v[2:17], v[198:201], v[206:209], v[2:17]
	s_waitcnt vmcnt(11)
	ds_write_b128 v129, v[66:69]
	s_waitcnt vmcnt(10)
	ds_write_b128 v129, v[70:73] offset:9216
	s_waitcnt vmcnt(9)
	ds_write_b128 v129, v[74:77] offset:18432
	s_waitcnt vmcnt(8)
	ds_write_b128 v129, v[78:81] offset:27648
	s_waitcnt vmcnt(7)
	ds_write_b128 v129, v[82:85] offset:36864
	s_waitcnt vmcnt(6)
	ds_write_b128 v129, v[86:89] offset:46080
	s_waitcnt lgkmcnt(0)
	s_barrier
	global_load_dwordx4 v[66:69], v[114:115], off offset:512
	global_load_dwordx4 v[70:73], v[118:119], off offset:512
	global_load_dwordx4 v[74:77], v[120:121], off offset:512
	global_load_dwordx4 v[78:81], v[122:123], off offset:512
	global_load_dwordx4 v[82:85], v[116:117], off offset:512
	global_load_dwordx4 v[86:89], v[124:125], off offset:512
	ds_read_b128 v[146:149], v127
	ds_read_b128 v[154:157], v132 offset:36864
	ds_read_b128 v[158:161], v132 offset:41472
	ds_read_b128 v[150:153], v127 offset:4608
	ds_read_b128 v[194:197], v127 offset:32
	ds_read_b128 v[202:205], v132 offset:36896
	ds_read_b128 v[206:209], v132 offset:41504
	ds_read_b128 v[198:201], v127 offset:4640
	s_waitcnt lgkmcnt(4)
	v_mfma_f32_32x32x16_bf16 v[50:65], v[146:149], v[154:157], v[50:65]
	v_mfma_f32_32x32x16_bf16 v[34:49], v[146:149], v[158:161], v[34:49]
	v_mfma_f32_32x32x16_bf16 v[18:33], v[150:153], v[154:157], v[18:33]
	v_mfma_f32_32x32x16_bf16 v[2:17], v[150:153], v[158:161], v[2:17]
	ds_read_b128 v[146:149], v127 offset:64
	ds_read_b128 v[154:157], v132 offset:36928
	ds_read_b128 v[158:161], v132 offset:41536
	ds_read_b128 v[150:153], v127 offset:4672
	s_waitcnt lgkmcnt(4)
	v_mfma_f32_32x32x16_bf16 v[50:65], v[194:197], v[202:205], v[50:65]
	v_mfma_f32_32x32x16_bf16 v[34:49], v[194:197], v[206:209], v[34:49]
	v_mfma_f32_32x32x16_bf16 v[18:33], v[198:201], v[202:205], v[18:33]
	v_mfma_f32_32x32x16_bf16 v[2:17], v[198:201], v[206:209], v[2:17]
	ds_read_b128 v[194:197], v127 offset:96
	ds_read_b128 v[202:205], v132 offset:36960
	ds_read_b128 v[206:209], v132 offset:41568
	ds_read_b128 v[198:201], v127 offset:4704
	s_waitcnt lgkmcnt(4)
	v_mfma_f32_32x32x16_bf16 v[50:65], v[146:149], v[154:157], v[50:65]
	v_mfma_f32_32x32x16_bf16 v[34:49], v[146:149], v[158:161], v[34:49]
	v_mfma_f32_32x32x16_bf16 v[18:33], v[150:153], v[154:157], v[18:33]
	v_mfma_f32_32x32x16_bf16 v[2:17], v[150:153], v[158:161], v[2:17]
	s_waitcnt lgkmcnt(0)
	v_mfma_f32_32x32x16_bf16 v[50:65], v[194:197], v[202:205], v[50:65]
	v_mfma_f32_32x32x16_bf16 v[34:49], v[194:197], v[206:209], v[34:49]
	v_mfma_f32_32x32x16_bf16 v[18:33], v[198:201], v[202:205], v[18:33]
	v_mfma_f32_32x32x16_bf16 v[2:17], v[198:201], v[206:209], v[2:17]
	s_waitcnt vmcnt(11)
	ds_write_b128 v129, v[90:93] offset:55296
	s_waitcnt vmcnt(10)
	ds_write_b128 v129, v[94:97] offset:64512
	s_waitcnt vmcnt(9)
	ds_write_b128 v131, v[98:101] offset:18432
	s_waitcnt vmcnt(8)
	ds_write_b128 v131, v[102:105] offset:27648
	s_waitcnt vmcnt(7)
	ds_write_b128 v130, v[106:109]
	s_waitcnt vmcnt(6)
	ds_write_b128 v130, v[110:113] offset:9216
	s_waitcnt lgkmcnt(0)
	s_barrier
; #define MFMA16(a, b, c) __builtin_amdgcn_mfma_f32_32x32x16_bf16((a), (b), (c), 0, 0, 0)
; #define G_LOADR(S, ko) do { S##0 = *(const uint4*)(a0p + (ko)); S##1 = *(const uint4*)(a1p + (ko)); S##2 = *(const uint4*)(a2p + (ko)); \
;     S##3 = *(const uint4*)(a3p + (ko)); S##4 = *(const uint4*)(b0p + (ko)); S##5 = *(const uint4*)(b1p + (ko)); } while (0)
; #define G_STORER(S, nb) do { *(uint4*)((nb) + wofs) = S##0; *(uint4*)((nb) + wofs + 64 * G_AST) = S##1; *(uint4*)((nb) + wofs + 128 * G_AST) = S##2; \
;     *(uint4*)((nb) + wofs + 192 * G_AST) = S##3; *(uint4*)((nb) + G_ABYTES + wofs) = S##4; *(uint4*)((nb) + G_ABYTES + wofs + 64 * G_AST) = S##5; } while (0)
; DI void gemm_compute(f32x16 (&acc)[2][2], const unsigned char* As, const unsigned char* Bs) {
;   bf16x8 a0 = *(const bf16x8*)(As), a1 = *(const bf16x8*)(As + 32 * G_AST);
;   bf16x8 b0 = *(const bf16x8*)(Bs), b1 = *(const bf16x8*)(Bs + 32 * G_AST);
; #pragma unroll
;   for (int ks = 0; ks < 4; ++ks) {
;     bf16x8 na0 = a0, na1 = a1, nb0 = b0, nb1 = b1;
;     if (ks < 3) {
;       na0 = *(const bf16x8*)(As + (ks + 1) * 32); na1 = *(const bf16x8*)(As + 32 * G_AST + (ks + 1) * 32);
;       nb0 = *(const bf16x8*)(Bs + (ks + 1) * 32); nb1 = *(const bf16x8*)(Bs + 32 * G_AST + (ks + 1) * 32);
;     }
;     acc[0][0] = MFMA16(a0, b0, acc[0][0]);
;     acc[0][1] = MFMA16(a0, b1, acc[0][1]);
;     acc[1][0] = MFMA16(a1, b0, acc[1][0]);
;     acc[1][1] = MFMA16(a1, b1, acc[1][1]);
;     a0 = na0; a1 = na1; b0 = nb0; b1 = nb1;
;   }
; }
; DI void gemm_main(f32x16 (&acc)[2][2], const u16* const (&ap)[4], const u16* const (&bp)[2], int K, unsigned char* lds) {
;     ...
;   for (int kt = 0; kt < nk; kt += 2) {
;     if (kt + 2 < nk) G_LOADR(P, (kt + 2) * 64);
;     __builtin_amdgcn_sched_barrier(0);
;     gemm_compute(acc, As0, Bs0);
;     __builtin_amdgcn_sched_barrier(0);
;     G_STORER(Q, lds + G_STAGE);
;     __syncthreads();
;     if (kt + 3 < nk) G_LOADR(Q, (kt + 3) * 64);
;     __builtin_amdgcn_sched_barrier(0);
;     gemm_compute(acc, As0 + G_STAGE, Bs0 + G_STAGE);
;     __builtin_amdgcn_sched_barrier(0);
;     if (kt + 2 < nk) G_STORER(P, lds);
;     __syncthreads();
	global_load_dwordx4 v[90:93], v[114:115], off offset:640
	global_load_dwordx4 v[94:97], v[118:119], off offset:640
	global_load_dwordx4 v[98:101], v[120:121], off offset:640
	global_load_dwordx4 v[102:105], v[122:123], off offset:640
	global_load_dwordx4 v[106:109], v[116:117], off offset:640
	global_load_dwordx4 v[110:113], v[124:125], off offset:640
	ds_read_b128 v[146:149], v127 offset:55296
	ds_read_b128 v[154:157], v128 offset:55296
	ds_read_b128 v[158:161], v128 offset:59904
	ds_read_b128 v[150:153], v127 offset:59904
	ds_read_b128 v[194:197], v127 offset:55328
	ds_read_b128 v[202:205], v128 offset:55328
	ds_read_b128 v[206:209], v128 offset:59936
	ds_read_b128 v[198:201], v127 offset:59936
	s_waitcnt lgkmcnt(4)
	v_mfma_f32_32x32x16_bf16 v[50:65], v[146:149], v[154:157], v[50:65]
	v_mfma_f32_32x32x16_bf16 v[34:49], v[146:149], v[158:161], v[34:49]
	v_mfma_f32_32x32x16_bf16 v[18:33], v[150:153], v[154:157], v[18:33]
	v_mfma_f32_32x32x16_bf16 v[2:17], v[150:153], v[158:161], v[2:17]
	ds_read_b128 v[146:149], v127 offset:55360
	ds_read_b128 v[154:157], v128 offset:55360
	ds_read_b128 v[158:161], v128 offset:59968
	ds_read_b128 v[150:153], v127 offset:59968
	s_waitcnt lgkmcnt(4)
	v_mfma_f32_32x32x16_bf16 v[50:65], v[194:197], v[202:205], v[50:65]
	v_mfma_f32_32x32x16_bf16 v[34:49], v[194:197], v[206:209], v[34:49]
	v_mfma_f32_32x32x16_bf16 v[18:33], v[198:201], v[202:205], v[18:33]
	v_mfma_f32_32x32x16_bf16 v[2:17], v[198:201], v[206:209], v[2:17]
	ds_read_b128 v[194:197], v127 offset:55392
	ds_read_b128 v[202:205], v128 offset:55392
	ds_read_b128 v[206:209], v128 offset:60000
	ds_read_b128 v[198:201], v127 offset:60000
	s_waitcnt lgkmcnt(4)
	v_mfma_f32_32x32x16_bf16 v[50:65], v[146:149], v[154:157], v[50:65]
	v_mfma_f32_32x32x16_bf16 v[34:49], v[146:149], v[158:161], v[34:49]
	v_mfma_f32_32x32x16_bf16 v[18:33], v[150:153], v[154:157], v[18:33]
	v_mfma_f32_32x32x16_bf16 v[2:17], v[150:153], v[158:161], v[2:17]
	s_waitcnt lgkmcnt(0)
	v_mfma_f32_32x32x16_bf16 v[50:65], v[194:197], v[202:205], v[50:65]
	v_mfma_f32_32x32x16_bf16 v[34:49], v[194:197], v[206:209], v[34:49]
	v_mfma_f32_32x32x16_bf16 v[18:33], v[198:201], v[202:205], v[18:33]
	v_mfma_f32_32x32x16_bf16 v[2:17], v[198:201], v[206:209], v[2:17]
	s_waitcnt vmcnt(11)
	ds_write_b128 v129, v[66:69]
	s_waitcnt vmcnt(10)
	ds_write_b128 v129, v[70:73] offset:9216
	s_waitcnt vmcnt(9)
	ds_write_b128 v129, v[74:77] offset:18432
	s_waitcnt vmcnt(8)
	ds_write_b128 v129, v[78:81] offset:27648
	s_waitcnt vmcnt(7)
	ds_write_b128 v129, v[82:85] offset:36864
	s_waitcnt vmcnt(6)
	ds_write_b128 v129, v[86:89] offset:46080
	s_waitcnt lgkmcnt(0)
	s_barrier
	global_load_dwordx4 v[66:69], v[114:115], off offset:768
	global_load_dwordx4 v[70:73], v[118:119], off offset:768
	global_load_dwordx4 v[74:77], v[120:121], off offset:768
	global_load_dwordx4 v[78:81], v[122:123], off offset:768
	global_load_dwordx4 v[82:85], v[116:117], off offset:768
	global_load_dwordx4 v[86:89], v[124:125], off offset:768
	ds_read_b128 v[146:149], v127
	ds_read_b128 v[154:157], v132 offset:36864
	ds_read_b128 v[158:161], v132 offset:41472
	ds_read_b128 v[150:153], v127 offset:4608
	ds_read_b128 v[194:197], v127 offset:32
	ds_read_b128 v[202:205], v132 offset:36896
	ds_read_b128 v[206:209], v132 offset:41504
	ds_read_b128 v[198:201], v127 offset:4640
	s_waitcnt lgkmcnt(4)
	v_mfma_f32_32x32x16_bf16 v[50:65], v[146:149], v[154:157], v[50:65]
	v_mfma_f32_32x32x16_bf16 v[34:49], v[146:149], v[158:161], v[34:49]
	v_mfma_f32_32x32x16_bf16 v[18:33], v[150:153], v[154:157], v[18:33]
	v_mfma_f32_32x32x16_bf16 v[2:17], v[150:153], v[158:161], v[2:17]
	ds_read_b128 v[146:149], v127 offset:64
	ds_read_b128 v[154:157], v132 offset:36928
	ds_read_b128 v[158:161], v132 offset:41536
	ds_read_b128 v[150:153], v127 offset:4672
	s_waitcnt lgkmcnt(4)
	v_mfma_f32_32x32x16_bf16 v[50:65], v[194:197], v[202:205], v[50:65]
	v_mfma_f32_32x32x16_bf16 v[34:49], v[194:197], v[206:209], v[34:49]
	v_mfma_f32_32x32x16_bf16 v[18:33], v[198:201], v[202:205], v[18:33]
	v_mfma_f32_32x32x16_bf16 v[2:17], v[198:201], v[206:209], v[2:17]
	ds_read_b128 v[194:197], v127 offset:96
	ds_read_b128 v[202:205], v132 offset:36960
	ds_read_b128 v[206:209], v132 offset:41568
	ds_read_b128 v[198:201], v127 offset:4704
	s_waitcnt lgkmcnt(4)
	v_mfma_f32_32x32x16_bf16 v[50:65], v[146:149], v[154:157], v[50:65]
	v_mfma_f32_32x32x16_bf16 v[34:49], v[146:149], v[158:161], v[34:49]
	v_mfma_f32_32x32x16_bf16 v[18:33], v[150:153], v[154:157], v[18:33]
	v_mfma_f32_32x32x16_bf16 v[2:17], v[150:153], v[158:161], v[2:17]
	s_waitcnt lgkmcnt(0)
	v_mfma_f32_32x32x16_bf16 v[50:65], v[194:197], v[202:205], v[50:65]
	v_mfma_f32_32x32x16_bf16 v[34:49], v[194:197], v[206:209], v[34:49]
	v_mfma_f32_32x32x16_bf16 v[18:33], v[198:201], v[202:205], v[18:33]
	v_mfma_f32_32x32x16_bf16 v[2:17], v[198:201], v[206:209], v[2:17]
	s_waitcnt vmcnt(11)
	ds_write_b128 v129, v[90:93] offset:55296
	s_waitcnt vmcnt(10)
	ds_write_b128 v129, v[94:97] offset:64512
	s_waitcnt vmcnt(9)
	ds_write_b128 v131, v[98:101] offset:18432
	s_waitcnt vmcnt(8)
	ds_write_b128 v131, v[102:105] offset:27648
	s_waitcnt vmcnt(7)
	ds_write_b128 v130, v[106:109]
	s_waitcnt vmcnt(6)
	ds_write_b128 v130, v[110:113] offset:9216
	s_waitcnt lgkmcnt(0)
	s_barrier
; #define MFMA16(a, b, c) __builtin_amdgcn_mfma_f32_32x32x16_bf16((a), (b), (c), 0, 0, 0)
; #define G_LOADR(S, ko) do { S##0 = *(const uint4*)(a0p + (ko)); S##1 = *(const uint4*)(a1p + (ko)); S##2 = *(const uint4*)(a2p + (ko)); \
;     S##3 = *(const uint4*)(a3p + (ko)); S##4 = *(const uint4*)(b0p + (ko)); S##5 = *(const uint4*)(b1p + (ko)); } while (0)
; #define G_STORER(S, nb) do { *(uint4*)((nb) + wofs) = S##0; *(uint4*)((nb) + wofs + 64 * G_AST) = S##1; *(uint4*)((nb) + wofs + 128 * G_AST) = S##2; \
;     *(uint4*)((nb) + wofs + 192 * G_AST) = S##3; *(uint4*)((nb) + G_ABYTES + wofs) = S##4; *(uint4*)((nb) + G_ABYTES + wofs + 64 * G_AST) = S##5; } while (0)
; DI void gemm_compute(f32x16 (&acc)[2][2], const unsigned char* As, const unsigned char* Bs) {
;   bf16x8 a0 = *(const bf16x8*)(As), a1 = *(const bf16x8*)(As + 32 * G_AST);
;   bf16x8 b0 = *(const bf16x8*)(Bs), b1 = *(const bf16x8*)(Bs + 32 * G_AST);
; #pragma unroll
;   for (int ks = 0; ks < 4; ++ks) {
;     bf16x8 na0 = a0, na1 = a1, nb0 = b0, nb1 = b1;
;     if (ks < 3) {
;       na0 = *(const bf16x8*)(As + (ks + 1) * 32); na1 = *(const bf16x8*)(As + 32 * G_AST + (ks + 1) * 32);
;       nb0 = *(const bf16x8*)(Bs + (ks + 1) * 32); nb1 = *(const bf16x8*)(Bs + 32 * G_AST + (ks + 1) * 32);
;     }
;     acc[0][0] = MFMA16(a0, b0, acc[0][0]);
;     acc[0][1] = MFMA16(a0, b1, acc[0][1]);
;     acc[1][0] = MFMA16(a1, b0, acc[1][0]);
;     acc[1][1] = MFMA16(a1, b1, acc[1][1]);
;     a0 = na0; a1 = na1; b0 = nb0; b1 = nb1;
;   }
; }
; DI void gemm_main(f32x16 (&acc)[2][2], const u16* const (&ap)[4], const u16* const (&bp)[2], int K, unsigned char* lds) {
;     ...
;   for (int kt = 0; kt < nk; kt += 2) {
;     if (kt + 2 < nk) G_LOADR(P, (kt + 2) * 64);
;     __builtin_amdgcn_sched_barrier(0);
;     gemm_compute(acc, As0, Bs0);
;     __builtin_amdgcn_sched_barrier(0);
;     G_STORER(Q, lds + G_STAGE);
;     __syncthreads();
;     if (kt + 3 < nk) G_LOADR(Q, (kt + 3) * 64);
;     __builtin_amdgcn_sched_barrier(0);
;     gemm_compute(acc, As0 + G_STAGE, Bs0 + G_STAGE);
;     __builtin_amdgcn_sched_barrier(0);
;     if (kt + 2 < nk) G_STORER(P, lds);
;     __syncthreads();
	global_load_dwordx4 v[90:93], v[114:115], off offset:896
	global_load_dwordx4 v[94:97], v[118:119], off offset:896
	global_load_dwordx4 v[98:101], v[120:121], off offset:896
	global_load_dwordx4 v[102:105], v[122:123], off offset:896
	global_load_dwordx4 v[106:109], v[116:117], off offset:896
	global_load_dwordx4 v[110:113], v[124:125], off offset:896
	ds_read_b128 v[146:149], v127 offset:55296
	ds_read_b128 v[154:157], v128 offset:55296
	ds_read_b128 v[158:161], v128 offset:59904
	ds_read_b128 v[150:153], v127 offset:59904
	ds_read_b128 v[194:197], v127 offset:55328
	ds_read_b128 v[202:205], v128 offset:55328
	ds_read_b128 v[206:209], v128 offset:59936
	ds_read_b128 v[198:201], v127 offset:59936
	s_waitcnt lgkmcnt(4)
	v_mfma_f32_32x32x16_bf16 v[50:65], v[146:149], v[154:157], v[50:65]
	v_mfma_f32_32x32x16_bf16 v[34:49], v[146:149], v[158:161], v[34:49]
	v_mfma_f32_32x32x16_bf16 v[18:33], v[150:153], v[154:157], v[18:33]
	v_mfma_f32_32x32x16_bf16 v[2:17], v[150:153], v[158:161], v[2:17]
	ds_read_b128 v[146:149], v127 offset:55360
	ds_read_b128 v[154:157], v128 offset:55360
	ds_read_b128 v[158:161], v128 offset:59968
	ds_read_b128 v[150:153], v127 offset:59968
	s_waitcnt lgkmcnt(4)
	v_mfma_f32_32x32x16_bf16 v[50:65], v[194:197], v[202:205], v[50:65]
	v_mfma_f32_32x32x16_bf16 v[34:49], v[194:197], v[206:209], v[34:49]
	v_mfma_f32_32x32x16_bf16 v[18:33], v[198:201], v[202:205], v[18:33]
	v_mfma_f32_32x32x16_bf16 v[2:17], v[198:201], v[206:209], v[2:17]
	ds_read_b128 v[194:197], v127 offset:55392
	ds_read_b128 v[202:205], v128 offset:55392
	ds_read_b128 v[206:209], v128 offset:60000
	ds_read_b128 v[198:201], v127 offset:60000
	s_waitcnt lgkmcnt(4)
	v_mfma_f32_32x32x16_bf16 v[50:65], v[146:149], v[154:157], v[50:65]
	v_mfma_f32_32x32x16_bf16 v[34:49], v[146:149], v[158:161], v[34:49]
	v_mfma_f32_32x32x16_bf16 v[18:33], v[150:153], v[154:157], v[18:33]
	v_mfma_f32_32x32x16_bf16 v[2:17], v[150:153], v[158:161], v[2:17]
	s_waitcnt lgkmcnt(0)
	v_mfma_f32_32x32x16_bf16 v[50:65], v[194:197], v[202:205], v[50:65]
	v_mfma_f32_32x32x16_bf16 v[34:49], v[194:197], v[206:209], v[34:49]
	v_mfma_f32_32x32x16_bf16 v[18:33], v[198:201], v[202:205], v[18:33]
	v_mfma_f32_32x32x16_bf16 v[2:17], v[198:201], v[206:209], v[2:17]
	s_waitcnt vmcnt(11)
	ds_write_b128 v129, v[66:69]
	s_waitcnt vmcnt(10)
	ds_write_b128 v129, v[70:73] offset:9216
	s_waitcnt vmcnt(9)
	ds_write_b128 v129, v[74:77] offset:18432
	s_waitcnt vmcnt(8)
	ds_write_b128 v129, v[78:81] offset:27648
	s_waitcnt vmcnt(7)
	ds_write_b128 v129, v[82:85] offset:36864
	s_waitcnt vmcnt(6)
	ds_write_b128 v129, v[86:89] offset:46080
	s_waitcnt lgkmcnt(0)
	s_barrier
	global_load_dwordx4 v[66:69], v[114:115], off offset:1024
	global_load_dwordx4 v[70:73], v[118:119], off offset:1024
	global_load_dwordx4 v[74:77], v[120:121], off offset:1024
	global_load_dwordx4 v[78:81], v[122:123], off offset:1024
	global_load_dwordx4 v[82:85], v[116:117], off offset:1024
	global_load_dwordx4 v[86:89], v[124:125], off offset:1024
	ds_read_b128 v[146:149], v127
	ds_read_b128 v[154:157], v132 offset:36864
	ds_read_b128 v[158:161], v132 offset:41472
	ds_read_b128 v[150:153], v127 offset:4608
	ds_read_b128 v[194:197], v127 offset:32
	ds_read_b128 v[202:205], v132 offset:36896
	ds_read_b128 v[206:209], v132 offset:41504
	ds_read_b128 v[198:201], v127 offset:4640
	s_waitcnt lgkmcnt(4)
	v_mfma_f32_32x32x16_bf16 v[50:65], v[146:149], v[154:157], v[50:65]
	v_mfma_f32_32x32x16_bf16 v[34:49], v[146:149], v[158:161], v[34:49]
	v_mfma_f32_32x32x16_bf16 v[18:33], v[150:153], v[154:157], v[18:33]
	v_mfma_f32_32x32x16_bf16 v[2:17], v[150:153], v[158:161], v[2:17]
	ds_read_b128 v[146:149], v127 offset:64
	ds_read_b128 v[154:157], v132 offset:36928
	ds_read_b128 v[158:161], v132 offset:41536
	ds_read_b128 v[150:153], v127 offset:4672
	s_waitcnt lgkmcnt(4)
	v_mfma_f32_32x32x16_bf16 v[50:65], v[194:197], v[202:205], v[50:65]
	v_mfma_f32_32x32x16_bf16 v[34:49], v[194:197], v[206:209], v[34:49]
	v_mfma_f32_32x32x16_bf16 v[18:33], v[198:201], v[202:205], v[18:33]
	v_mfma_f32_32x32x16_bf16 v[2:17], v[198:201], v[206:209], v[2:17]
	ds_read_b128 v[194:197], v127 offset:96
	ds_read_b128 v[202:205], v132 offset:36960
	ds_read_b128 v[206:209], v132 offset:41568
	ds_read_b128 v[198:201], v127 offset:4704
	s_waitcnt lgkmcnt(4)
	v_mfma_f32_32x32x16_bf16 v[50:65], v[146:149], v[154:157], v[50:65]
	v_mfma_f32_32x32x16_bf16 v[34:49], v[146:149], v[158:161], v[34:49]
	v_mfma_f32_32x32x16_bf16 v[18:33], v[150:153], v[154:157], v[18:33]
	v_mfma_f32_32x32x16_bf16 v[2:17], v[150:153], v[158:161], v[2:17]
	s_waitcnt lgkmcnt(0)
	v_mfma_f32_32x32x16_bf16 v[50:65], v[194:197], v[202:205], v[50:65]
	v_mfma_f32_32x32x16_bf16 v[34:49], v[194:197], v[206:209], v[34:49]
	v_mfma_f32_32x32x16_bf16 v[18:33], v[198:201], v[202:205], v[18:33]
	v_mfma_f32_32x32x16_bf16 v[2:17], v[198:201], v[206:209], v[2:17]
	s_waitcnt vmcnt(11)
	ds_write_b128 v129, v[90:93] offset:55296
	s_waitcnt vmcnt(10)
	ds_write_b128 v129, v[94:97] offset:64512
	s_waitcnt vmcnt(9)
	ds_write_b128 v131, v[98:101] offset:18432
	s_waitcnt vmcnt(8)
	ds_write_b128 v131, v[102:105] offset:27648
	s_waitcnt vmcnt(7)
	ds_write_b128 v130, v[106:109]
	s_waitcnt vmcnt(6)
	ds_write_b128 v130, v[110:113] offset:9216
	s_waitcnt lgkmcnt(0)
	s_barrier
; #define MFMA16(a, b, c) __builtin_amdgcn_mfma_f32_32x32x16_bf16((a), (b), (c), 0, 0, 0)
; #define G_LOADR(S, ko) do { S##0 = *(const uint4*)(a0p + (ko)); S##1 = *(const uint4*)(a1p + (ko)); S##2 = *(const uint4*)(a2p + (ko)); \
;     S##3 = *(const uint4*)(a3p + (ko)); S##4 = *(const uint4*)(b0p + (ko)); S##5 = *(const uint4*)(b1p + (ko)); } while (0)
; #define G_STORER(S, nb) do { *(uint4*)((nb) + wofs) = S##0; *(uint4*)((nb) + wofs + 64 * G_AST) = S##1; *(uint4*)((nb) + wofs + 128 * G_AST) = S##2; \
;     *(uint4*)((nb) + wofs + 192 * G_AST) = S##3; *(uint4*)((nb) + G_ABYTES + wofs) = S##4; *(uint4*)((nb) + G_ABYTES + wofs + 64 * G_AST) = S##5; } while (0)
; DI void gemm_compute(f32x16 (&acc)[2][2], const unsigned char* As, const unsigned char* Bs) {
;   bf16x8 a0 = *(const bf16x8*)(As), a1 = *(const bf16x8*)(As + 32 * G_AST);
;   bf16x8 b0 = *(const bf16x8*)(Bs), b1 = *(const bf16x8*)(Bs + 32 * G_AST);
; #pragma unroll
;   for (int ks = 0; ks < 4; ++ks) {
;     bf16x8 na0 = a0, na1 = a1, nb0 = b0, nb1 = b1;
;     if (ks < 3) {
;       na0 = *(const bf16x8*)(As + (ks + 1) * 32); na1 = *(const bf16x8*)(As + 32 * G_AST + (ks + 1) * 32);
;       nb0 = *(const bf16x8*)(Bs + (ks + 1) * 32); nb1 = *(const bf16x8*)(Bs + 32 * G_AST + (ks + 1) * 32);
;     }
;     acc[0][0] = MFMA16(a0, b0, acc[0][0]);
;     acc[0][1] = MFMA16(a0, b1, acc[0][1]);
;     acc[1][0] = MFMA16(a1, b0, acc[1][0]);
;     acc[1][1] = MFMA16(a1, b1, acc[1][1]);
;     a0 = na0; a1 = na1; b0 = nb0; b1 = nb1;
;   }
; }
; DI void gemm_main(f32x16 (&acc)[2][2], const u16* const (&ap)[4], const u16* const (&bp)[2], int K, unsigned char* lds) {
;     ...
;   for (int kt = 0; kt < nk; kt += 2) {
;     if (kt + 2 < nk) G_LOADR(P, (kt + 2) * 64);
;     __builtin_amdgcn_sched_barrier(0);
;     gemm_compute(acc, As0, Bs0);
;     __builtin_amdgcn_sched_barrier(0);
;     G_STORER(Q, lds + G_STAGE);
;     __syncthreads();
;     if (kt + 3 < nk) G_LOADR(Q, (kt + 3) * 64);
;     __builtin_amdgcn_sched_barrier(0);
;     gemm_compute(acc, As0 + G_STAGE, Bs0 + G_STAGE);
;     __builtin_amdgcn_sched_barrier(0);
;     if (kt + 2 < nk) G_STORER(P, lds);
;     __syncthreads();
	global_load_dwordx4 v[90:93], v[114:115], off offset:1152
	global_load_dwordx4 v[94:97], v[118:119], off offset:1152
	global_load_dwordx4 v[98:101], v[120:121], off offset:1152
	global_load_dwordx4 v[102:105], v[122:123], off offset:1152
	global_load_dwordx4 v[106:109], v[116:117], off offset:1152
	global_load_dwordx4 v[110:113], v[124:125], off offset:1152
	ds_read_b128 v[146:149], v127 offset:55296
	ds_read_b128 v[154:157], v128 offset:55296
	ds_read_b128 v[158:161], v128 offset:59904
	ds_read_b128 v[150:153], v127 offset:59904
	ds_read_b128 v[194:197], v127 offset:55328
	ds_read_b128 v[202:205], v128 offset:55328
	ds_read_b128 v[206:209], v128 offset:59936
	ds_read_b128 v[198:201], v127 offset:59936
	s_waitcnt lgkmcnt(4)
	v_mfma_f32_32x32x16_bf16 v[50:65], v[146:149], v[154:157], v[50:65]
	v_mfma_f32_32x32x16_bf16 v[34:49], v[146:149], v[158:161], v[34:49]
	v_mfma_f32_32x32x16_bf16 v[18:33], v[150:153], v[154:157], v[18:33]
	v_mfma_f32_32x32x16_bf16 v[2:17], v[150:153], v[158:161], v[2:17]
	ds_read_b128 v[146:149], v127 offset:55360
	ds_read_b128 v[154:157], v128 offset:55360
	ds_read_b128 v[158:161], v128 offset:59968
	ds_read_b128 v[150:153], v127 offset:59968
	s_waitcnt lgkmcnt(4)
	v_mfma_f32_32x32x16_bf16 v[50:65], v[194:197], v[202:205], v[50:65]
	v_mfma_f32_32x32x16_bf16 v[34:49], v[194:197], v[206:209], v[34:49]
	v_mfma_f32_32x32x16_bf16 v[18:33], v[198:201], v[202:205], v[18:33]
	v_mfma_f32_32x32x16_bf16 v[2:17], v[198:201], v[206:209], v[2:17]
	ds_read_b128 v[194:197], v127 offset:55392
	ds_read_b128 v[202:205], v128 offset:55392
	ds_read_b128 v[206:209], v128 offset:60000
	ds_read_b128 v[198:201], v127 offset:60000
	s_waitcnt lgkmcnt(4)
	v_mfma_f32_32x32x16_bf16 v[50:65], v[146:149], v[154:157], v[50:65]
	v_mfma_f32_32x32x16_bf16 v[34:49], v[146:149], v[158:161], v[34:49]
	v_mfma_f32_32x32x16_bf16 v[18:33], v[150:153], v[154:157], v[18:33]
	v_mfma_f32_32x32x16_bf16 v[2:17], v[150:153], v[158:161], v[2:17]
	s_waitcnt lgkmcnt(0)
	v_mfma_f32_32x32x16_bf16 v[50:65], v[194:197], v[202:205], v[50:65]
	v_mfma_f32_32x32x16_bf16 v[34:49], v[194:197], v[206:209], v[34:49]
	v_mfma_f32_32x32x16_bf16 v[18:33], v[198:201], v[202:205], v[18:33]
	v_mfma_f32_32x32x16_bf16 v[2:17], v[198:201], v[206:209], v[2:17]
	s_waitcnt vmcnt(11)
	ds_write_b128 v129, v[66:69]
	s_waitcnt vmcnt(10)
	ds_write_b128 v129, v[70:73] offset:9216
	s_waitcnt vmcnt(9)
	ds_write_b128 v129, v[74:77] offset:18432
	s_waitcnt vmcnt(8)
	ds_write_b128 v129, v[78:81] offset:27648
	s_waitcnt vmcnt(7)
	ds_write_b128 v129, v[82:85] offset:36864
	s_waitcnt vmcnt(6)
	ds_write_b128 v129, v[86:89] offset:46080
	s_waitcnt lgkmcnt(0)
	s_barrier
	global_load_dwordx4 v[66:69], v[114:115], off offset:1280
	global_load_dwordx4 v[70:73], v[118:119], off offset:1280
	global_load_dwordx4 v[74:77], v[120:121], off offset:1280
	global_load_dwordx4 v[78:81], v[122:123], off offset:1280
	global_load_dwordx4 v[82:85], v[116:117], off offset:1280
	global_load_dwordx4 v[86:89], v[124:125], off offset:1280
	ds_read_b128 v[146:149], v127
	ds_read_b128 v[154:157], v132 offset:36864
	ds_read_b128 v[158:161], v132 offset:41472
	ds_read_b128 v[150:153], v127 offset:4608
	ds_read_b128 v[194:197], v127 offset:32
	ds_read_b128 v[202:205], v132 offset:36896
	ds_read_b128 v[206:209], v132 offset:41504
	ds_read_b128 v[198:201], v127 offset:4640
	s_waitcnt lgkmcnt(4)
	v_mfma_f32_32x32x16_bf16 v[50:65], v[146:149], v[154:157], v[50:65]
	v_mfma_f32_32x32x16_bf16 v[34:49], v[146:149], v[158:161], v[34:49]
	v_mfma_f32_32x32x16_bf16 v[18:33], v[150:153], v[154:157], v[18:33]
	v_mfma_f32_32x32x16_bf16 v[2:17], v[150:153], v[158:161], v[2:17]
	ds_read_b128 v[146:149], v127 offset:64
	ds_read_b128 v[154:157], v132 offset:36928
	ds_read_b128 v[158:161], v132 offset:41536
	ds_read_b128 v[150:153], v127 offset:4672
	s_waitcnt lgkmcnt(4)
	v_mfma_f32_32x32x16_bf16 v[50:65], v[194:197], v[202:205], v[50:65]
	v_mfma_f32_32x32x16_bf16 v[34:49], v[194:197], v[206:209], v[34:49]
	v_mfma_f32_32x32x16_bf16 v[18:33], v[198:201], v[202:205], v[18:33]
	v_mfma_f32_32x32x16_bf16 v[2:17], v[198:201], v[206:209], v[2:17]
	ds_read_b128 v[194:197], v127 offset:96
	ds_read_b128 v[202:205], v132 offset:36960
	ds_read_b128 v[206:209], v132 offset:41568
	ds_read_b128 v[198:201], v127 offset:4704
	s_waitcnt lgkmcnt(4)
	v_mfma_f32_32x32x16_bf16 v[50:65], v[146:149], v[154:157], v[50:65]
	v_mfma_f32_32x32x16_bf16 v[34:49], v[146:149], v[158:161], v[34:49]
	v_mfma_f32_32x32x16_bf16 v[18:33], v[150:153], v[154:157], v[18:33]
	v_mfma_f32_32x32x16_bf16 v[2:17], v[150:153], v[158:161], v[2:17]
	s_waitcnt lgkmcnt(0)
	v_mfma_f32_32x32x16_bf16 v[50:65], v[194:197], v[202:205], v[50:65]
	v_mfma_f32_32x32x16_bf16 v[34:49], v[194:197], v[206:209], v[34:49]
	v_mfma_f32_32x32x16_bf16 v[18:33], v[198:201], v[202:205], v[18:33]
	v_mfma_f32_32x32x16_bf16 v[2:17], v[198:201], v[206:209], v[2:17]
	s_waitcnt vmcnt(11)
	ds_write_b128 v129, v[90:93] offset:55296
	s_waitcnt vmcnt(10)
	ds_write_b128 v129, v[94:97] offset:64512
	s_waitcnt vmcnt(9)
	ds_write_b128 v131, v[98:101] offset:18432
	s_waitcnt vmcnt(8)
	ds_write_b128 v131, v[102:105] offset:27648
	s_waitcnt vmcnt(7)
	ds_write_b128 v130, v[106:109]
	s_waitcnt vmcnt(6)
	ds_write_b128 v130, v[110:113] offset:9216
	s_waitcnt lgkmcnt(0)
	s_barrier
; #define MFMA16(a, b, c) __builtin_amdgcn_mfma_f32_32x32x16_bf16((a), (b), (c), 0, 0, 0)
; #define G_LOADR(S, ko) do { S##0 = *(const uint4*)(a0p + (ko)); S##1 = *(const uint4*)(a1p + (ko)); S##2 = *(const uint4*)(a2p + (ko)); \
;     S##3 = *(const uint4*)(a3p + (ko)); S##4 = *(const uint4*)(b0p + (ko)); S##5 = *(const uint4*)(b1p + (ko)); } while (0)
; #define G_STORER(S, nb) do { *(uint4*)((nb) + wofs) = S##0; *(uint4*)((nb) + wofs + 64 * G_AST) = S##1; *(uint4*)((nb) + wofs + 128 * G_AST) = S##2; \
;     *(uint4*)((nb) + wofs + 192 * G_AST) = S##3; *(uint4*)((nb) + G_ABYTES + wofs) = S##4; *(uint4*)((nb) + G_ABYTES + wofs + 64 * G_AST) = S##5; } while (0)
; DI void gemm_compute(f32x16 (&acc)[2][2], const unsigned char* As, const unsigned char* Bs) {
;   bf16x8 a0 = *(const bf16x8*)(As), a1 = *(const bf16x8*)(As + 32 * G_AST);
;   bf16x8 b0 = *(const bf16x8*)(Bs), b1 = *(const bf16x8*)(Bs + 32 * G_AST);
; #pragma unroll
;   for (int ks = 0; ks < 4; ++ks) {
;     bf16x8 na0 = a0, na1 = a1, nb0 = b0, nb1 = b1;
;     if (ks < 3) {
;       na0 = *(const bf16x8*)(As + (ks + 1) * 32); na1 = *(const bf16x8*)(As + 32 * G_AST + (ks + 1) * 32);
;       nb0 = *(const bf16x8*)(Bs + (ks + 1) * 32); nb1 = *(const bf16x8*)(Bs + 32 * G_AST + (ks + 1) * 32);
;     }
;     acc[0][0] = MFMA16(a0, b0, acc[0][0]);
;     acc[0][1] = MFMA16(a0, b1, acc[0][1]);
;     acc[1][0] = MFMA16(a1, b0, acc[1][0]);
;     acc[1][1] = MFMA16(a1, b1, acc[1][1]);
;     a0 = na0; a1 = na1; b0 = nb0; b1 = nb1;
;   }
; }
; DI void gemm_main(f32x16 (&acc)[2][2], const u16* const (&ap)[4], const u16* const (&bp)[2], int K, unsigned char* lds) {
;     ...
;   for (int kt = 0; kt < nk; kt += 2) {
;     if (kt + 2 < nk) G_LOADR(P, (kt + 2) * 64);
;     __builtin_amdgcn_sched_barrier(0);
;     gemm_compute(acc, As0, Bs0);
;     __builtin_amdgcn_sched_barrier(0);
;     G_STORER(Q, lds + G_STAGE);
;     __syncthreads();
;     if (kt + 3 < nk) G_LOADR(Q, (kt + 3) * 64);
;     __builtin_amdgcn_sched_barrier(0);
;     gemm_compute(acc, As0 + G_STAGE, Bs0 + G_STAGE);
;     __builtin_amdgcn_sched_barrier(0);
;     if (kt + 2 < nk) G_STORER(P, lds);
;     __syncthreads();
	global_load_dwordx4 v[90:93], v[114:115], off offset:1408
	global_load_dwordx4 v[94:97], v[118:119], off offset:1408
	global_load_dwordx4 v[98:101], v[120:121], off offset:1408
	global_load_dwordx4 v[102:105], v[122:123], off offset:1408
	global_load_dwordx4 v[106:109], v[116:117], off offset:1408
	global_load_dwordx4 v[110:113], v[124:125], off offset:1408
	ds_read_b128 v[146:149], v127 offset:55296
	ds_read_b128 v[154:157], v128 offset:55296
	ds_read_b128 v[158:161], v128 offset:59904
	ds_read_b128 v[150:153], v127 offset:59904
	ds_read_b128 v[194:197], v127 offset:55328
	ds_read_b128 v[202:205], v128 offset:55328
	ds_read_b128 v[206:209], v128 offset:59936
	ds_read_b128 v[198:201], v127 offset:59936
	s_waitcnt lgkmcnt(4)
	v_mfma_f32_32x32x16_bf16 v[50:65], v[146:149], v[154:157], v[50:65]
	v_mfma_f32_32x32x16_bf16 v[34:49], v[146:149], v[158:161], v[34:49]
	v_mfma_f32_32x32x16_bf16 v[18:33], v[150:153], v[154:157], v[18:33]
	v_mfma_f32_32x32x16_bf16 v[2:17], v[150:153], v[158:161], v[2:17]
	ds_read_b128 v[146:149], v127 offset:55360
	ds_read_b128 v[154:157], v128 offset:55360
	ds_read_b128 v[158:161], v128 offset:59968
	ds_read_b128 v[150:153], v127 offset:59968
	s_waitcnt lgkmcnt(4)
	v_mfma_f32_32x32x16_bf16 v[50:65], v[194:197], v[202:205], v[50:65]
	v_mfma_f32_32x32x16_bf16 v[34:49], v[194:197], v[206:209], v[34:49]
	v_mfma_f32_32x32x16_bf16 v[18:33], v[198:201], v[202:205], v[18:33]
	v_mfma_f32_32x32x16_bf16 v[2:17], v[198:201], v[206:209], v[2:17]
	ds_read_b128 v[194:197], v127 offset:55392
	ds_read_b128 v[202:205], v128 offset:55392
	ds_read_b128 v[206:209], v128 offset:60000
	ds_read_b128 v[198:201], v127 offset:60000
	s_waitcnt lgkmcnt(4)
	v_mfma_f32_32x32x16_bf16 v[50:65], v[146:149], v[154:157], v[50:65]
	v_mfma_f32_32x32x16_bf16 v[34:49], v[146:149], v[158:161], v[34:49]
	v_mfma_f32_32x32x16_bf16 v[18:33], v[150:153], v[154:157], v[18:33]
	v_mfma_f32_32x32x16_bf16 v[2:17], v[150:153], v[158:161], v[2:17]
	s_waitcnt lgkmcnt(0)
	v_mfma_f32_32x32x16_bf16 v[50:65], v[194:197], v[202:205], v[50:65]
	v_mfma_f32_32x32x16_bf16 v[34:49], v[194:197], v[206:209], v[34:49]
	v_mfma_f32_32x32x16_bf16 v[18:33], v[198:201], v[202:205], v[18:33]
	v_mfma_f32_32x32x16_bf16 v[2:17], v[198:201], v[206:209], v[2:17]
	s_waitcnt vmcnt(11)
	ds_write_b128 v129, v[66:69]
	s_waitcnt vmcnt(10)
	ds_write_b128 v129, v[70:73] offset:9216
	s_waitcnt vmcnt(9)
	ds_write_b128 v129, v[74:77] offset:18432
	s_waitcnt vmcnt(8)
	ds_write_b128 v129, v[78:81] offset:27648
	s_waitcnt vmcnt(7)
	ds_write_b128 v129, v[82:85] offset:36864
	s_waitcnt vmcnt(6)
	ds_write_b128 v129, v[86:89] offset:46080
	s_waitcnt lgkmcnt(0)
	s_barrier
	global_load_dwordx4 v[66:69], v[114:115], off offset:1536
	global_load_dwordx4 v[70:73], v[118:119], off offset:1536
	global_load_dwordx4 v[74:77], v[120:121], off offset:1536
	global_load_dwordx4 v[78:81], v[122:123], off offset:1536
	global_load_dwordx4 v[82:85], v[116:117], off offset:1536
	global_load_dwordx4 v[86:89], v[124:125], off offset:1536
	ds_read_b128 v[146:149], v127
	ds_read_b128 v[154:157], v132 offset:36864
	ds_read_b128 v[158:161], v132 offset:41472
	ds_read_b128 v[150:153], v127 offset:4608
	ds_read_b128 v[194:197], v127 offset:32
	ds_read_b128 v[202:205], v132 offset:36896
	ds_read_b128 v[206:209], v132 offset:41504
	ds_read_b128 v[198:201], v127 offset:4640
	s_waitcnt lgkmcnt(4)
	v_mfma_f32_32x32x16_bf16 v[50:65], v[146:149], v[154:157], v[50:65]
	v_mfma_f32_32x32x16_bf16 v[34:49], v[146:149], v[158:161], v[34:49]
	v_mfma_f32_32x32x16_bf16 v[18:33], v[150:153], v[154:157], v[18:33]
	v_mfma_f32_32x32x16_bf16 v[2:17], v[150:153], v[158:161], v[2:17]
	ds_read_b128 v[146:149], v127 offset:64
	ds_read_b128 v[154:157], v132 offset:36928
	ds_read_b128 v[158:161], v132 offset:41536
	ds_read_b128 v[150:153], v127 offset:4672
	s_waitcnt lgkmcnt(4)
	v_mfma_f32_32x32x16_bf16 v[50:65], v[194:197], v[202:205], v[50:65]
	v_mfma_f32_32x32x16_bf16 v[34:49], v[194:197], v[206:209], v[34:49]
	v_mfma_f32_32x32x16_bf16 v[18:33], v[198:201], v[202:205], v[18:33]
	v_mfma_f32_32x32x16_bf16 v[2:17], v[198:201], v[206:209], v[2:17]
	ds_read_b128 v[194:197], v127 offset:96
	ds_read_b128 v[202:205], v132 offset:36960
	ds_read_b128 v[206:209], v132 offset:41568
	ds_read_b128 v[198:201], v127 offset:4704
	s_waitcnt lgkmcnt(4)
	v_mfma_f32_32x32x16_bf16 v[50:65], v[146:149], v[154:157], v[50:65]
	v_mfma_f32_32x32x16_bf16 v[34:49], v[146:149], v[158:161], v[34:49]
	v_mfma_f32_32x32x16_bf16 v[18:33], v[150:153], v[154:157], v[18:33]
	v_mfma_f32_32x32x16_bf16 v[2:17], v[150:153], v[158:161], v[2:17]
	s_waitcnt lgkmcnt(0)
	v_mfma_f32_32x32x16_bf16 v[50:65], v[194:197], v[202:205], v[50:65]
	v_mfma_f32_32x32x16_bf16 v[34:49], v[194:197], v[206:209], v[34:49]
	v_mfma_f32_32x32x16_bf16 v[18:33], v[198:201], v[202:205], v[18:33]
	v_mfma_f32_32x32x16_bf16 v[2:17], v[198:201], v[206:209], v[2:17]
	s_waitcnt vmcnt(11)
	ds_write_b128 v129, v[90:93] offset:55296
	s_waitcnt vmcnt(10)
	ds_write_b128 v129, v[94:97] offset:64512
	s_waitcnt vmcnt(9)
	ds_write_b128 v131, v[98:101] offset:18432
	s_waitcnt vmcnt(8)
	ds_write_b128 v131, v[102:105] offset:27648
	s_waitcnt vmcnt(7)
	ds_write_b128 v130, v[106:109]
	s_waitcnt vmcnt(6)
	ds_write_b128 v130, v[110:113] offset:9216
	s_waitcnt lgkmcnt(0)
	s_barrier
; #define MFMA16(a, b, c) __builtin_amdgcn_mfma_f32_32x32x16_bf16((a), (b), (c), 0, 0, 0)
; #define G_LOADR(S, ko) do { S##0 = *(const uint4*)(a0p + (ko)); S##1 = *(const uint4*)(a1p + (ko)); S##2 = *(const uint4*)(a2p + (ko)); \
;     S##3 = *(const uint4*)(a3p + (ko)); S##4 = *(const uint4*)(b0p + (ko)); S##5 = *(const uint4*)(b1p + (ko)); } while (0)
; #define G_STORER(S, nb) do { *(uint4*)((nb) + wofs) = S##0; *(uint4*)((nb) + wofs + 64 * G_AST) = S##1; *(uint4*)((nb) + wofs + 128 * G_AST) = S##2; \
;     *(uint4*)((nb) + wofs + 192 * G_AST) = S##3; *(uint4*)((nb) + G_ABYTES + wofs) = S##4; *(uint4*)((nb) + G_ABYTES + wofs + 64 * G_AST) = S##5; } while (0)
; DI void gemm_compute(f32x16 (&acc)[2][2], const unsigned char* As, const unsigned char* Bs) {
;   bf16x8 a0 = *(const bf16x8*)(As), a1 = *(const bf16x8*)(As + 32 * G_AST);
;   bf16x8 b0 = *(const bf16x8*)(Bs), b1 = *(const bf16x8*)(Bs + 32 * G_AST);
; #pragma unroll
;   for (int ks = 0; ks < 4; ++ks) {
;     bf16x8 na0 = a0, na1 = a1, nb0 = b0, nb1 = b1;
;     if (ks < 3) {
;       na0 = *(const bf16x8*)(As + (ks + 1) * 32); na1 = *(const bf16x8*)(As + 32 * G_AST + (ks + 1) * 32);
;       nb0 = *(const bf16x8*)(Bs + (ks + 1) * 32); nb1 = *(const bf16x8*)(Bs + 32 * G_AST + (ks + 1) * 32);
;     }
;     acc[0][0] = MFMA16(a0, b0, acc[0][0]);
;     acc[0][1] = MFMA16(a0, b1, acc[0][1]);
;     acc[1][0] = MFMA16(a1, b0, acc[1][0]);
;     acc[1][1] = MFMA16(a1, b1, acc[1][1]);
;     a0 = na0; a1 = na1; b0 = nb0; b1 = nb1;
;   }
; }
; DI void gemm_main(f32x16 (&acc)[2][2], const u16* const (&ap)[4], const u16* const (&bp)[2], int K, unsigned char* lds) {
;     ...
;   for (int kt = 0; kt < nk; kt += 2) {
;     if (kt + 2 < nk) G_LOADR(P, (kt + 2) * 64);
;     __builtin_amdgcn_sched_barrier(0);
;     gemm_compute(acc, As0, Bs0);
;     __builtin_amdgcn_sched_barrier(0);
;     G_STORER(Q, lds + G_STAGE);
;     __syncthreads();
;     if (kt + 3 < nk) G_LOADR(Q, (kt + 3) * 64);
;     __builtin_amdgcn_sched_barrier(0);
;     gemm_compute(acc, As0 + G_STAGE, Bs0 + G_STAGE);
;     __builtin_amdgcn_sched_barrier(0);
;     if (kt + 2 < nk) G_STORER(P, lds);
;     __syncthreads();
	global_load_dwordx4 v[90:93], v[114:115], off offset:1664
	global_load_dwordx4 v[94:97], v[118:119], off offset:1664
	global_load_dwordx4 v[98:101], v[120:121], off offset:1664
	global_load_dwordx4 v[102:105], v[122:123], off offset:1664
	global_load_dwordx4 v[106:109], v[116:117], off offset:1664
	global_load_dwordx4 v[110:113], v[124:125], off offset:1664
	ds_read_b128 v[146:149], v127 offset:55296
	ds_read_b128 v[154:157], v128 offset:55296
	ds_read_b128 v[158:161], v128 offset:59904
	ds_read_b128 v[150:153], v127 offset:59904
	ds_read_b128 v[194:197], v127 offset:55328
	ds_read_b128 v[202:205], v128 offset:55328
	ds_read_b128 v[206:209], v128 offset:59936
	ds_read_b128 v[198:201], v127 offset:59936
	s_waitcnt lgkmcnt(4)
	v_mfma_f32_32x32x16_bf16 v[50:65], v[146:149], v[154:157], v[50:65]
	v_mfma_f32_32x32x16_bf16 v[34:49], v[146:149], v[158:161], v[34:49]
	v_mfma_f32_32x32x16_bf16 v[18:33], v[150:153], v[154:157], v[18:33]
	v_mfma_f32_32x32x16_bf16 v[2:17], v[150:153], v[158:161], v[2:17]
	ds_read_b128 v[146:149], v127 offset:55360
	ds_read_b128 v[154:157], v128 offset:55360
	ds_read_b128 v[158:161], v128 offset:59968
	ds_read_b128 v[150:153], v127 offset:59968
	s_waitcnt lgkmcnt(4)
	v_mfma_f32_32x32x16_bf16 v[50:65], v[194:197], v[202:205], v[50:65]
	v_mfma_f32_32x32x16_bf16 v[34:49], v[194:197], v[206:209], v[34:49]
	v_mfma_f32_32x32x16_bf16 v[18:33], v[198:201], v[202:205], v[18:33]
	v_mfma_f32_32x32x16_bf16 v[2:17], v[198:201], v[206:209], v[2:17]
	ds_read_b128 v[194:197], v127 offset:55392
	ds_read_b128 v[202:205], v128 offset:55392
	ds_read_b128 v[206:209], v128 offset:60000
	ds_read_b128 v[198:201], v127 offset:60000
	s_waitcnt lgkmcnt(4)
	v_mfma_f32_32x32x16_bf16 v[50:65], v[146:149], v[154:157], v[50:65]
	v_mfma_f32_32x32x16_bf16 v[34:49], v[146:149], v[158:161], v[34:49]
	v_mfma_f32_32x32x16_bf16 v[18:33], v[150:153], v[154:157], v[18:33]
	v_mfma_f32_32x32x16_bf16 v[2:17], v[150:153], v[158:161], v[2:17]
	s_waitcnt lgkmcnt(0)
	v_mfma_f32_32x32x16_bf16 v[50:65], v[194:197], v[202:205], v[50:65]
	v_mfma_f32_32x32x16_bf16 v[34:49], v[194:197], v[206:209], v[34:49]
	v_mfma_f32_32x32x16_bf16 v[18:33], v[198:201], v[202:205], v[18:33]
	v_mfma_f32_32x32x16_bf16 v[2:17], v[198:201], v[206:209], v[2:17]
	s_waitcnt vmcnt(11)
	ds_write_b128 v129, v[66:69]
	s_waitcnt vmcnt(10)
	ds_write_b128 v129, v[70:73] offset:9216
	s_waitcnt vmcnt(9)
	ds_write_b128 v129, v[74:77] offset:18432
	s_waitcnt vmcnt(8)
	ds_write_b128 v129, v[78:81] offset:27648
	s_waitcnt vmcnt(7)
	ds_write_b128 v129, v[82:85] offset:36864
	s_waitcnt vmcnt(6)
	ds_write_b128 v129, v[86:89] offset:46080
	s_waitcnt lgkmcnt(0)
	s_barrier
	global_load_dwordx4 v[66:69], v[114:115], off offset:1792
	global_load_dwordx4 v[70:73], v[118:119], off offset:1792
	global_load_dwordx4 v[74:77], v[120:121], off offset:1792
	global_load_dwordx4 v[78:81], v[122:123], off offset:1792
	global_load_dwordx4 v[82:85], v[116:117], off offset:1792
	global_load_dwordx4 v[86:89], v[124:125], off offset:1792
	ds_read_b128 v[146:149], v127
	ds_read_b128 v[154:157], v132 offset:36864
	ds_read_b128 v[158:161], v132 offset:41472
	ds_read_b128 v[150:153], v127 offset:4608
	ds_read_b128 v[194:197], v127 offset:32
	ds_read_b128 v[202:205], v132 offset:36896
	ds_read_b128 v[206:209], v132 offset:41504
	ds_read_b128 v[198:201], v127 offset:4640
	s_waitcnt lgkmcnt(4)
	v_mfma_f32_32x32x16_bf16 v[50:65], v[146:149], v[154:157], v[50:65]
	v_mfma_f32_32x32x16_bf16 v[34:49], v[146:149], v[158:161], v[34:49]
	v_mfma_f32_32x32x16_bf16 v[18:33], v[150:153], v[154:157], v[18:33]
	v_mfma_f32_32x32x16_bf16 v[2:17], v[150:153], v[158:161], v[2:17]
	ds_read_b128 v[146:149], v127 offset:64
	ds_read_b128 v[154:157], v132 offset:36928
	ds_read_b128 v[158:161], v132 offset:41536
	ds_read_b128 v[150:153], v127 offset:4672
	s_waitcnt lgkmcnt(4)
	v_mfma_f32_32x32x16_bf16 v[50:65], v[194:197], v[202:205], v[50:65]
	v_mfma_f32_32x32x16_bf16 v[34:49], v[194:197], v[206:209], v[34:49]
	v_mfma_f32_32x32x16_bf16 v[18:33], v[198:201], v[202:205], v[18:33]
	v_mfma_f32_32x32x16_bf16 v[2:17], v[198:201], v[206:209], v[2:17]
	ds_read_b128 v[194:197], v127 offset:96
	ds_read_b128 v[202:205], v132 offset:36960
	ds_read_b128 v[206:209], v132 offset:41568
	ds_read_b128 v[198:201], v127 offset:4704
	s_waitcnt lgkmcnt(4)
	v_mfma_f32_32x32x16_bf16 v[50:65], v[146:149], v[154:157], v[50:65]
	v_mfma_f32_32x32x16_bf16 v[34:49], v[146:149], v[158:161], v[34:49]
	v_mfma_f32_32x32x16_bf16 v[18:33], v[150:153], v[154:157], v[18:33]
	v_mfma_f32_32x32x16_bf16 v[2:17], v[150:153], v[158:161], v[2:17]
	s_waitcnt lgkmcnt(0)
	v_mfma_f32_32x32x16_bf16 v[50:65], v[194:197], v[202:205], v[50:65]
	v_mfma_f32_32x32x16_bf16 v[34:49], v[194:197], v[206:209], v[34:49]
	v_mfma_f32_32x32x16_bf16 v[18:33], v[198:201], v[202:205], v[18:33]
	v_mfma_f32_32x32x16_bf16 v[2:17], v[198:201], v[206:209], v[2:17]
	s_waitcnt vmcnt(11)
	ds_write_b128 v129, v[90:93] offset:55296
	s_waitcnt vmcnt(10)
	ds_write_b128 v129, v[94:97] offset:64512
	s_waitcnt vmcnt(9)
	ds_write_b128 v131, v[98:101] offset:18432
	s_waitcnt vmcnt(8)
	ds_write_b128 v131, v[102:105] offset:27648
	s_waitcnt vmcnt(7)
	ds_write_b128 v130, v[106:109]
	s_waitcnt vmcnt(6)
	ds_write_b128 v130, v[110:113] offset:9216
	s_waitcnt lgkmcnt(0)
	s_barrier
; #define MFMA16(a, b, c) __builtin_amdgcn_mfma_f32_32x32x16_bf16((a), (b), (c), 0, 0, 0)
; #define G_LOADR(S, ko) do { S##0 = *(const uint4*)(a0p + (ko)); S##1 = *(const uint4*)(a1p + (ko)); S##2 = *(const uint4*)(a2p + (ko)); \
;     S##3 = *(const uint4*)(a3p + (ko)); S##4 = *(const uint4*)(b0p + (ko)); S##5 = *(const uint4*)(b1p + (ko)); } while (0)
; #define G_STORER(S, nb) do { *(uint4*)((nb) + wofs) = S##0; *(uint4*)((nb) + wofs + 64 * G_AST) = S##1; *(uint4*)((nb) + wofs + 128 * G_AST) = S##2; \
;     *(uint4*)((nb) + wofs + 192 * G_AST) = S##3; *(uint4*)((nb) + G_ABYTES + wofs) = S##4; *(uint4*)((nb) + G_ABYTES + wofs + 64 * G_AST) = S##5; } while (0)
; DI void gemm_compute(f32x16 (&acc)[2][2], const unsigned char* As, const unsigned char* Bs) {
;   bf16x8 a0 = *(const bf16x8*)(As), a1 = *(const bf16x8*)(As + 32 * G_AST);
;   bf16x8 b0 = *(const bf16x8*)(Bs), b1 = *(const bf16x8*)(Bs + 32 * G_AST);
; #pragma unroll
;   for (int ks = 0; ks < 4; ++ks) {
;     bf16x8 na0 = a0, na1 = a1, nb0 = b0, nb1 = b1;
;     if (ks < 3) {
;       na0 = *(const bf16x8*)(As + (ks + 1) * 32); na1 = *(const bf16x8*)(As + 32 * G_AST + (ks + 1) * 32);
;       nb0 = *(const bf16x8*)(Bs + (ks + 1) * 32); nb1 = *(const bf16x8*)(Bs + 32 * G_AST + (ks + 1) * 32);
;     }
;     acc[0][0] = MFMA16(a0, b0, acc[0][0]);
;     acc[0][1] = MFMA16(a0, b1, acc[0][1]);
;     acc[1][0] = MFMA16(a1, b0, acc[1][0]);
;     acc[1][1] = MFMA16(a1, b1, acc[1][1]);
;     a0 = na0; a1 = na1; b0 = nb0; b1 = nb1;
;   }
; }
; DI void gemm_main(f32x16 (&acc)[2][2], const u16* const (&ap)[4], const u16* const (&bp)[2], int K, unsigned char* lds) {
;     ...
;   for (int kt = 0; kt < nk; kt += 2) {
;     if (kt + 2 < nk) G_LOADR(P, (kt + 2) * 64);
;     __builtin_amdgcn_sched_barrier(0);
;     gemm_compute(acc, As0, Bs0);
;     __builtin_amdgcn_sched_barrier(0);
;     G_STORER(Q, lds + G_STAGE);
;     __syncthreads();
;     if (kt + 3 < nk) G_LOADR(Q, (kt + 3) * 64);
;     __builtin_amdgcn_sched_barrier(0);
;     gemm_compute(acc, As0 + G_STAGE, Bs0 + G_STAGE);
;     __builtin_amdgcn_sched_barrier(0);
;     if (kt + 2 < nk) G_STORER(P, lds);
;     __syncthreads();
	global_load_dwordx4 v[90:93], v[114:115], off offset:1920
	global_load_dwordx4 v[94:97], v[118:119], off offset:1920
	global_load_dwordx4 v[98:101], v[120:121], off offset:1920
	global_load_dwordx4 v[102:105], v[122:123], off offset:1920
	global_load_dwordx4 v[106:109], v[116:117], off offset:1920
	global_load_dwordx4 v[110:113], v[124:125], off offset:1920
	ds_read_b128 v[146:149], v127 offset:55296
	ds_read_b128 v[154:157], v128 offset:55296
	ds_read_b128 v[158:161], v128 offset:59904
	ds_read_b128 v[150:153], v127 offset:59904
	ds_read_b128 v[194:197], v127 offset:55328
	ds_read_b128 v[202:205], v128 offset:55328
	ds_read_b128 v[206:209], v128 offset:59936
	ds_read_b128 v[198:201], v127 offset:59936
	s_waitcnt lgkmcnt(4)
	v_mfma_f32_32x32x16_bf16 v[50:65], v[146:149], v[154:157], v[50:65]
	v_mfma_f32_32x32x16_bf16 v[34:49], v[146:149], v[158:161], v[34:49]
	v_mfma_f32_32x32x16_bf16 v[18:33], v[150:153], v[154:157], v[18:33]
	v_mfma_f32_32x32x16_bf16 v[2:17], v[150:153], v[158:161], v[2:17]
	ds_read_b128 v[146:149], v127 offset:55360
	ds_read_b128 v[154:157], v128 offset:55360
	ds_read_b128 v[158:161], v128 offset:59968
	ds_read_b128 v[150:153], v127 offset:59968
	s_waitcnt lgkmcnt(4)
	v_mfma_f32_32x32x16_bf16 v[50:65], v[194:197], v[202:205], v[50:65]
	v_mfma_f32_32x32x16_bf16 v[34:49], v[194:197], v[206:209], v[34:49]
	v_mfma_f32_32x32x16_bf16 v[18:33], v[198:201], v[202:205], v[18:33]
	v_mfma_f32_32x32x16_bf16 v[2:17], v[198:201], v[206:209], v[2:17]
	ds_read_b128 v[194:197], v127 offset:55392
	ds_read_b128 v[202:205], v128 offset:55392
	ds_read_b128 v[206:209], v128 offset:60000
	ds_read_b128 v[198:201], v127 offset:60000
	s_waitcnt lgkmcnt(4)
	v_mfma_f32_32x32x16_bf16 v[50:65], v[146:149], v[154:157], v[50:65]
	v_mfma_f32_32x32x16_bf16 v[34:49], v[146:149], v[158:161], v[34:49]
	v_mfma_f32_32x32x16_bf16 v[18:33], v[150:153], v[154:157], v[18:33]
	v_mfma_f32_32x32x16_bf16 v[2:17], v[150:153], v[158:161], v[2:17]
	s_waitcnt lgkmcnt(0)
	v_mfma_f32_32x32x16_bf16 v[50:65], v[194:197], v[202:205], v[50:65]
	v_mfma_f32_32x32x16_bf16 v[34:49], v[194:197], v[206:209], v[34:49]
	v_mfma_f32_32x32x16_bf16 v[18:33], v[198:201], v[202:205], v[18:33]
	v_mfma_f32_32x32x16_bf16 v[2:17], v[198:201], v[206:209], v[2:17]
	s_waitcnt vmcnt(11)
	ds_write_b128 v129, v[66:69]
	s_waitcnt vmcnt(10)
	ds_write_b128 v129, v[70:73] offset:9216
	s_waitcnt vmcnt(9)
	ds_write_b128 v129, v[74:77] offset:18432
	s_waitcnt vmcnt(8)
	ds_write_b128 v129, v[78:81] offset:27648
	s_waitcnt vmcnt(7)
	ds_write_b128 v129, v[82:85] offset:36864
	s_waitcnt vmcnt(6)
	ds_write_b128 v129, v[86:89] offset:46080
	s_waitcnt lgkmcnt(0)
	s_barrier
; #define MFMA16(a, b, c) __builtin_amdgcn_mfma_f32_32x32x16_bf16((a), (b), (c), 0, 0, 0)
; DI int crow(int i, int hh) { return (i & 3) + 8 * (i >> 2) + 4 * hh; }
; DI void gemm_compute(f32x16 (&acc)[2][2], const unsigned char* As, const unsigned char* Bs) {
;   bf16x8 a0 = *(const bf16x8*)(As), a1 = *(const bf16x8*)(As + 32 * G_AST);
;   bf16x8 b0 = *(const bf16x8*)(Bs), b1 = *(const bf16x8*)(Bs + 32 * G_AST);
; #pragma unroll
;   for (int ks = 0; ks < 4; ++ks) {
;     bf16x8 na0 = a0, na1 = a1, nb0 = b0, nb1 = b1;
;     if (ks < 3) {
;       na0 = *(const bf16x8*)(As + (ks + 1) * 32); na1 = *(const bf16x8*)(As + 32 * G_AST + (ks + 1) * 32);
;       nb0 = *(const bf16x8*)(Bs + (ks + 1) * 32); nb1 = *(const bf16x8*)(Bs + 32 * G_AST + (ks + 1) * 32);
;     }
;     acc[0][0] = MFMA16(a0, b0, acc[0][0]);
;     acc[0][1] = MFMA16(a0, b1, acc[0][1]);
;     acc[1][0] = MFMA16(a1, b0, acc[1][0]);
;     acc[1][1] = MFMA16(a1, b1, acc[1][1]);
;     a0 = na0; a1 = na1; b0 = nb0; b1 = nb1;
;   }
; }
; DI void wo_phase(const P& p, int l, int rows, unsigned char* lds) {
;     ...
; #pragma unroll
;     for (int mt = 0; mt < 2; ++mt)
; #pragma unroll
;       for (int nt = 0; nt < 2; ++nt)
; #pragma unroll
;         for (int i = 0; i < 16; ++i) {
;           int row = m0 + wm * 64 + mt * 32 + crow(i, hh), col = n0 + wn * 64 + nt * 32 + r;
;           float xin;
;           if (l == 0) xin = row < T ? p.in[I_X][(size_t)row * D + col] : p.in[I_CTX][(size_t)(row - T) * D + col];
;           else xin = XA[(size_t)row * D + col];
;           int mr = row < T ? (row >> 13) : 4;
;           XA[(size_t)row * D + col] = xin + MOD[mr * 6144 + 2 * 1024 + col] * acc[mt][nt][i];
	ds_read_b128 v[146:149], v127
	ds_read_b128 v[154:157], v132 offset:36864
	ds_read_b128 v[158:161], v132 offset:41472
	ds_read_b128 v[150:153], v127 offset:4608
	ds_read_b128 v[194:197], v127 offset:32
	ds_read_b128 v[202:205], v132 offset:36896
	ds_read_b128 v[206:209], v132 offset:41504
	ds_read_b128 v[198:201], v127 offset:4640
	s_waitcnt lgkmcnt(4)
	v_mfma_f32_32x32x16_bf16 v[50:65], v[146:149], v[154:157], v[50:65]
	v_mfma_f32_32x32x16_bf16 v[34:49], v[146:149], v[158:161], v[34:49]
	v_mfma_f32_32x32x16_bf16 v[18:33], v[150:153], v[154:157], v[18:33]
	v_mfma_f32_32x32x16_bf16 v[2:17], v[150:153], v[158:161], v[2:17]
	ds_read_b128 v[146:149], v127 offset:64
	ds_read_b128 v[154:157], v132 offset:36928
	ds_read_b128 v[158:161], v132 offset:41536
	ds_read_b128 v[150:153], v127 offset:4672
	s_waitcnt lgkmcnt(4)
	v_mfma_f32_32x32x16_bf16 v[50:65], v[194:197], v[202:205], v[50:65]
	v_mfma_f32_32x32x16_bf16 v[34:49], v[194:197], v[206:209], v[34:49]
	v_mfma_f32_32x32x16_bf16 v[18:33], v[198:201], v[202:205], v[18:33]
	v_mfma_f32_32x32x16_bf16 v[2:17], v[198:201], v[206:209], v[2:17]
	ds_read_b128 v[194:197], v127 offset:96
	ds_read_b128 v[202:205], v132 offset:36960
	ds_read_b128 v[206:209], v132 offset:41568
	ds_read_b128 v[198:201], v127 offset:4704
	s_waitcnt lgkmcnt(4)
	v_mfma_f32_32x32x16_bf16 v[50:65], v[146:149], v[154:157], v[50:65]
	v_mfma_f32_32x32x16_bf16 v[34:49], v[146:149], v[158:161], v[34:49]
	v_mfma_f32_32x32x16_bf16 v[18:33], v[150:153], v[154:157], v[18:33]
	v_mfma_f32_32x32x16_bf16 v[2:17], v[150:153], v[158:161], v[2:17]
	s_waitcnt lgkmcnt(0)
	v_mfma_f32_32x32x16_bf16 v[50:65], v[194:197], v[202:205], v[50:65]
	v_mfma_f32_32x32x16_bf16 v[34:49], v[194:197], v[206:209], v[34:49]
	v_mfma_f32_32x32x16_bf16 v[18:33], v[198:201], v[202:205], v[18:33]
	v_mfma_f32_32x32x16_bf16 v[2:17], v[198:201], v[206:209], v[2:17]
	s_waitcnt vmcnt(5)
	ds_write_b128 v129, v[90:93] offset:55296
	s_waitcnt vmcnt(4)
	ds_write_b128 v129, v[94:97] offset:64512
	s_waitcnt vmcnt(3)
	ds_write_b128 v131, v[98:101] offset:18432
	s_waitcnt vmcnt(2)
	ds_write_b128 v131, v[102:105] offset:27648
	s_waitcnt vmcnt(1)
	ds_write_b128 v130, v[106:109]
	s_waitcnt vmcnt(0)
	ds_write_b128 v130, v[110:113] offset:9216
	s_waitcnt lgkmcnt(0)
	s_barrier
	ds_read_b128 v[146:149], v127 offset:55296
	ds_read_b128 v[154:157], v128 offset:55296
	ds_read_b128 v[158:161], v128 offset:59904
	ds_read_b128 v[150:153], v127 offset:59904
	ds_read_b128 v[194:197], v127 offset:55328
	ds_read_b128 v[202:205], v128 offset:55328
	ds_read_b128 v[206:209], v128 offset:59936
	ds_read_b128 v[198:201], v127 offset:59936
	s_waitcnt lgkmcnt(4)
	v_mfma_f32_32x32x16_bf16 v[50:65], v[146:149], v[154:157], v[50:65]
	v_mfma_f32_32x32x16_bf16 v[34:49], v[146:149], v[158:161], v[34:49]
	v_mfma_f32_32x32x16_bf16 v[18:33], v[150:153], v[154:157], v[18:33]
	v_mfma_f32_32x32x16_bf16 v[2:17], v[150:153], v[158:161], v[2:17]
	ds_read_b128 v[146:149], v127 offset:55360
	ds_read_b128 v[154:157], v128 offset:55360
	ds_read_b128 v[158:161], v128 offset:59968
	ds_read_b128 v[150:153], v127 offset:59968
	s_waitcnt lgkmcnt(4)
	v_mfma_f32_32x32x16_bf16 v[50:65], v[194:197], v[202:205], v[50:65]
	v_mfma_f32_32x32x16_bf16 v[34:49], v[194:197], v[206:209], v[34:49]
	v_mfma_f32_32x32x16_bf16 v[18:33], v[198:201], v[202:205], v[18:33]
	v_mfma_f32_32x32x16_bf16 v[2:17], v[198:201], v[206:209], v[2:17]
	ds_read_b128 v[194:197], v127 offset:55392
	ds_read_b128 v[202:205], v128 offset:55392
	ds_read_b128 v[206:209], v128 offset:60000
	ds_read_b128 v[198:201], v127 offset:60000
	s_waitcnt lgkmcnt(4)
	v_mfma_f32_32x32x16_bf16 v[50:65], v[146:149], v[154:157], v[50:65]
	v_mfma_f32_32x32x16_bf16 v[34:49], v[146:149], v[158:161], v[34:49]
	v_mfma_f32_32x32x16_bf16 v[18:33], v[150:153], v[154:157], v[18:33]
	v_mfma_f32_32x32x16_bf16 v[2:17], v[150:153], v[158:161], v[2:17]
	s_waitcnt lgkmcnt(0)
	v_mfma_f32_32x32x16_bf16 v[50:65], v[194:197], v[202:205], v[50:65]
	v_mfma_f32_32x32x16_bf16 v[34:49], v[194:197], v[206:209], v[34:49]
	v_mfma_f32_32x32x16_bf16 v[18:33], v[198:201], v[202:205], v[18:33]
	v_mfma_f32_32x32x16_bf16 v[2:17], v[198:201], v[206:209], v[2:17]
	v_readlane_b32 s4, v254, 52
	v_or_b32_e32 v66, s0, v126
	v_readlane_b32 s5, v254, 53
	v_ashrrev_i32_e32 v67, 31, v66
	v_add_u32_e32 v70, s11, v1
	s_mov_b64 s[0:1], -1
	s_and_b64 vcc, exec, s[4:5]
	s_barrier
	s_lshl_b32 s0, s11, 12
	s_add_u32 s4, s86, s0
	s_addc_u32 s5, s87, 0
	v_readlane_b32 s12, v254, 52
	v_readlane_b32 s13, v254, 53
	v_lshlrev_b32_e32 v241, 2, v66
	v_lshl_add_u32 v240, v1, 12, v241
	s_cmp_lg_u64 s[12:13], 0
	s_cbranch_scc1 .Lwo_src_xa
	s_cmp_gt_i32 s11, s15
	s_cbranch_scc1 .Lwo_src_ctx
	s_add_u32 s12, s68, s0
	s_addc_u32 s13, s69, 0
	s_branch .Lwo_src_done
